# nt (streaming) hint on read-once loads: weight conversion in the scan phase and x rows in the prologue; light L2-prefetch helpers; 1-deep scan loaders
# speedup vs baseline: 1.0266x; 1.0114x over previous
.LBB0_26:
	s_cmpk_gt_i32 s26, 0x3fff
	s_mov_b64 s[16:17], -1
	s_cbranch_scc1 .LBB0_25
	v_add_co_u32_e32 v34, vcc, 0x2000, v102
	global_load_dwordx4 v[90:93], v[102:103], off nt
	global_load_dwordx4 v[82:85], v[102:103], off offset:1024 nt
	global_load_dwordx4 v[74:77], v[102:103], off offset:2048 nt
	global_load_dwordx4 v[66:69], v[102:103], off offset:3072 nt
	s_waitcnt lgkmcnt(0)
	v_addc_co_u32_e32 v35, vcc, 0, v103, vcc
	global_load_dwordx4 v[94:97], v[34:35], off nt
	global_load_dwordx4 v[86:89], v[34:35], off offset:1024 nt
	global_load_dwordx4 v[78:81], v[34:35], off offset:2048 nt
	global_load_dwordx4 v[70:73], v[34:35], off offset:3072 nt
	v_add_co_u32_e32 v34, vcc, 0x1000, v102
	s_waitcnt vmcnt(7)
	v_mul_f32_e32 v104, v91, v91
	v_addc_co_u32_e32 v35, vcc, 0, v103, vcc
	global_load_dwordx4 v[58:61], v[34:35], off nt
	v_add_co_u32_e32 v36, vcc, 0x3000, v102
	v_mul_f32_e32 v105, v93, v93
	s_nop 0
	v_addc_co_u32_e32 v37, vcc, 0, v103, vcc
	global_load_dwordx4 v[62:65], v[36:37], off nt
	global_load_dwordx4 v[54:57], v[34:35], off offset:1024 nt
	global_load_dwordx4 v[50:53], v[36:37], off offset:1024 nt
	global_load_dwordx4 v[46:49], v[34:35], off offset:2048 nt
	global_load_dwordx4 v[42:45], v[36:37], off offset:2048 nt
	global_load_dwordx4 v[38:41], v[34:35], off offset:3072 nt
	s_nop 0
	global_load_dwordx4 v[34:37], v[36:37], off offset:3072 nt
	s_waitcnt vmcnt(14)
	v_mul_f32_e32 v106, v83, v83
	v_mul_f32_e32 v107, v85, v85
	s_waitcnt vmcnt(13)
	v_mul_f32_e32 v108, v75, v75
	v_mul_f32_e32 v109, v77, v77
	s_waitcnt vmcnt(12)
	v_mul_f32_e32 v110, v67, v67
	v_mul_f32_e32 v111, v69, v69
	v_fmac_f32_e32 v104, v90, v90
	v_fmac_f32_e32 v105, v92, v92
	v_fmac_f32_e32 v106, v82, v82
	v_fmac_f32_e32 v107, v84, v84
	v_fmac_f32_e32 v108, v74, v74
	v_fmac_f32_e32 v109, v76, v76
	v_fmac_f32_e32 v110, v66, v66
	v_fmac_f32_e32 v111, v68, v68
	v_add_f32_e32 v104, v104, v105
	s_waitcnt vmcnt(11)
	v_mul_f32_e32 v105, v95, v95
	v_mul_f32_e32 v112, v97, v97
	v_add_f32_e32 v106, v106, v107
	s_waitcnt vmcnt(10)
	v_mul_f32_e32 v107, v87, v87
	v_mul_f32_e32 v113, v89, v89
	v_add_f32_e32 v108, v108, v109
	s_waitcnt vmcnt(9)
	v_mul_f32_e32 v109, v79, v79
	v_mul_f32_e32 v114, v81, v81
	v_add_f32_e32 v110, v110, v111
	s_waitcnt vmcnt(8)
	v_mul_f32_e32 v111, v71, v71
	v_mul_f32_e32 v115, v73, v73
	v_fmac_f32_e32 v105, v94, v94
	v_fmac_f32_e32 v112, v96, v96
	v_fmac_f32_e32 v107, v86, v86
	v_fmac_f32_e32 v113, v88, v88
	v_add_f32_e32 v104, v104, v106
	v_fmac_f32_e32 v109, v78, v78
	v_fmac_f32_e32 v114, v80, v80
	v_fmac_f32_e32 v111, v70, v70
	v_fmac_f32_e32 v115, v72, v72
	v_add_f32_e32 v105, v105, v112
	v_add_f32_e32 v107, v107, v113
	v_add_f32_e32 v104, v104, v108
	v_add_f32_e32 v108, v109, v114
	v_add_f32_e32 v109, v111, v115
	v_add_f32_e32 v105, v105, v107
	v_add_f32_e32 v104, v104, v110
	v_add_f32_e32 v105, v105, v108
	v_add_f32_e32 v105, v105, v109
	s_waitcnt vmcnt(7)
	v_mul_f32_e32 v106, v59, v59
	v_mul_f32_e32 v116, v61, v61
	v_fmac_f32_e32 v106, v58, v58
	v_fmac_f32_e32 v116, v60, v60
	s_waitcnt vmcnt(6)
	v_mul_f32_e32 v111, v63, v63
	v_mul_f32_e32 v112, v65, v65
	v_add_f32_e32 v106, v106, v116
	v_fmac_f32_e32 v111, v62, v62
	v_fmac_f32_e32 v112, v64, v64
	v_add_f32_e32 v104, v104, v106
	v_add_f32_e32 v106, v111, v112
	v_add_f32_e32 v105, v105, v106
	s_waitcnt vmcnt(5)
	v_mul_f32_e32 v106, v55, v55
	v_mul_f32_e32 v107, v57, v57
	v_fmac_f32_e32 v106, v54, v54
	v_fmac_f32_e32 v107, v56, v56
	v_add_f32_e32 v106, v106, v107
	v_add_f32_e32 v104, v104, v106
	s_waitcnt vmcnt(4)
	v_mul_f32_e32 v106, v51, v51
	v_mul_f32_e32 v107, v53, v53
	v_fmac_f32_e32 v106, v50, v50
	v_fmac_f32_e32 v107, v52, v52
	v_add_f32_e32 v106, v106, v107
	v_add_f32_e32 v105, v105, v106
	s_waitcnt vmcnt(3)
	v_mul_f32_e32 v106, v47, v47
	v_mul_f32_e32 v107, v49, v49
	v_fmac_f32_e32 v106, v46, v46
	v_fmac_f32_e32 v107, v48, v48
	v_add_f32_e32 v106, v106, v107
	v_add_f32_e32 v104, v104, v106
	s_waitcnt vmcnt(2)
	v_mul_f32_e32 v106, v43, v43
	v_mul_f32_e32 v107, v45, v45
	v_fmac_f32_e32 v106, v42, v42
	v_fmac_f32_e32 v107, v44, v44
	v_add_f32_e32 v106, v106, v107
	v_add_f32_e32 v105, v105, v106
	s_waitcnt vmcnt(1)
	v_mul_f32_e32 v106, v39, v39
	v_mul_f32_e32 v107, v41, v41
	v_fmac_f32_e32 v106, v38, v38
	v_fmac_f32_e32 v107, v40, v40
	v_add_f32_e32 v106, v106, v107
	v_add_f32_e32 v104, v104, v106
	v_mov_b32_e32 v106, 0
	s_waitcnt vmcnt(0)
	v_mul_f32_e32 v107, v35, v35
	v_add_f32_dpp v104, v104, v104 quad_perm:[1,0,3,2] row_mask:0xf bank_mask:0xf bound_ctrl:1
	v_mul_f32_e32 v108, v37, v37
	v_fmac_f32_e32 v107, v34, v34
	v_add_f32_dpp v104, v104, v104 quad_perm:[2,3,0,1] row_mask:0xf bank_mask:0xf bound_ctrl:1
	v_fmac_f32_e32 v108, v36, v36
	v_add_f32_e32 v107, v107, v108
	v_add_f32_dpp v104, v104, v104 row_half_mirror row_mask:0xf bank_mask:0xf bound_ctrl:1
	v_add_f32_e32 v105, v105, v107
	s_nop 0
	v_add_f32_dpp v104, v104, v104 row_mirror row_mask:0xf bank_mask:0xf bound_ctrl:1
	v_add_f32_dpp v105, v105, v105 quad_perm:[1,0,3,2] row_mask:0xf bank_mask:0xf bound_ctrl:1
	s_nop 0
	v_mov_b32_dpp v106, v104 row_bcast:15 row_mask:0xa bank_mask:0xf
	v_add_f32_e32 v104, v104, v106
	v_mov_b32_e32 v106, 0
	v_add_f32_dpp v105, v105, v105 quad_perm:[2,3,0,1] row_mask:0xf bank_mask:0xf bound_ctrl:1
	s_nop 0
	v_mov_b32_dpp v106, v104 row_bcast:31 row_mask:0xc bank_mask:0xf
	v_add_f32_e32 v104, v104, v106
	v_add_f32_dpp v105, v105, v105 row_half_mirror row_mask:0xf bank_mask:0xf bound_ctrl:1
	v_readlane_b32 s2, v104, 63
	s_nop 0
	v_add_f32_dpp v105, v105, v105 row_mirror row_mask:0xf bank_mask:0xf bound_ctrl:1
	v_fma_f32 v104, s2, v187, v185
	v_mul_f32_e32 v106, 0x4f800000, v104
	v_cmp_gt_f32_e32 vcc, s3, v104
	s_nop 1
	v_cndmask_b32_e32 v104, v104, v106, vcc
	v_sqrt_f32_e32 v106, v104
	s_nop 0
	v_add_u32_e32 v109, -1, v106
	v_fma_f32 v110, -v109, v106, v104
	v_cmp_ge_f32_e64 s[16:17], 0, v110
	v_add_u32_e32 v110, 1, v106
	s_nop 0
	v_cndmask_b32_e64 v109, v106, v109, s[16:17]
	v_fma_f32 v106, -v110, v106, v104
	v_cmp_lt_f32_e64 s[16:17], 0, v106
	s_nop 1
	v_cndmask_b32_e64 v106, v109, v110, s[16:17]
	v_mul_f32_e32 v109, 0x37800000, v106
	v_mov_b32_e32 v110, 0
	v_cndmask_b32_e32 v106, v106, v109, vcc
	v_cmp_class_f32_e32 vcc, v104, v186
	v_mov_b32_dpp v110, v105 row_bcast:15 row_mask:0xa bank_mask:0xf
	v_add_f32_e32 v105, v105, v110
	v_cndmask_b32_e32 v104, v106, v104, vcc
	v_mov_b32_e32 v110, 0
	v_div_scale_f32 v106, s[16:17], v104, v104, 1.0
	s_nop 0
	v_mov_b32_dpp v110, v105 row_bcast:31 row_mask:0xc bank_mask:0xf
	v_rcp_f32_e32 v109, v106
	v_add_f32_e32 v105, v105, v110
	v_fma_f32 v107, -v106, v109, 1.0
	v_readlane_b32 s2, v105, 63
	v_fmac_f32_e32 v109, v107, v109
	v_div_scale_f32 v107, vcc, 1.0, v104, 1.0
	v_fma_f32 v105, s2, v187, v185
	v_mul_f32_e32 v110, 0x4f800000, v105
	v_cmp_gt_f32_e64 s[16:17], s3, v105
	v_mul_f32_e32 v108, v107, v109
	v_fma_f32 v111, -v106, v108, v107
	v_cndmask_b32_e64 v105, v105, v110, s[16:17]
	v_sqrt_f32_e32 v110, v105
	v_fmac_f32_e32 v108, v111, v109
	v_fma_f32 v106, -v106, v108, v107
	v_div_fmas_f32 v106, v106, v109, v108
	v_add_u32_e32 v107, -1, v110
	v_fma_f32 v111, -v107, v110, v105
	v_cmp_ge_f32_e64 s[18:19], 0, v111
	v_add_u32_e32 v111, 1, v110
	v_div_fixup_f32 v118, v106, v104, 1.0
	v_cndmask_b32_e64 v107, v110, v107, s[18:19]
	v_fma_f32 v110, -v111, v110, v105
	v_cmp_lt_f32_e64 s[18:19], 0, v110
	v_pk_mul_f32 v[90:91], v[118:119], v[90:91] op_sel_hi:[0,1]
	v_pk_mul_f32 v[92:93], v[118:119], v[92:93] op_sel_hi:[0,1]
	v_cndmask_b32_e64 v107, v107, v111, s[18:19]
	v_mul_f32_e32 v110, 0x37800000, v107
	v_cndmask_b32_e64 v107, v107, v110, s[16:17]
	v_cmp_class_f32_e64 s[16:17], v105, v186
	v_pk_mul_f32 v[82:83], v[118:119], v[82:83] op_sel_hi:[0,1]
	v_pk_mul_f32 v[84:85], v[118:119], v[84:85] op_sel_hi:[0,1]
	v_cndmask_b32_e64 v105, v107, v105, s[16:17]
	v_div_scale_f32 v107, s[16:17], v105, v105, 1.0
	v_rcp_f32_e32 v110, v107
	v_pk_mul_f32 v[74:75], v[118:119], v[74:75] op_sel_hi:[0,1]
	v_pk_mul_f32 v[76:77], v[118:119], v[76:77] op_sel_hi:[0,1]
	v_pk_mul_f32 v[76:77], v[76:77], v[12:13]
	v_fma_f32 v104, -v107, v110, 1.0
	v_fmac_f32_e32 v110, v104, v110
	v_div_scale_f32 v104, vcc, 1.0, v105, 1.0
	v_mul_f32_e32 v106, v104, v110
	v_fma_f32 v108, -v107, v106, v104
	v_fmac_f32_e32 v106, v108, v110
	v_fma_f32 v104, -v107, v106, v104
	v_div_fmas_f32 v104, v104, v110, v106
	v_div_fixup_f32 v116, v104, v105, 1.0
	v_pk_mul_f32 v[106:107], v[90:91], v[2:3]
	v_pk_mul_f32 v[90:91], v[116:117], v[94:95] op_sel_hi:[0,1]
	v_pk_mul_f32 v[94:95], v[2:3], v[90:91]
	v_bfe_u32 v90, v106, 16, 1
	v_add3_u32 v90, v106, v90, s27
	v_bfe_u32 v91, v107, 16, 1
	v_pk_mul_f32 v[104:105], v[92:93], v[4:5]
	v_lshrrev_b32_e32 v90, 16, v90
	v_add3_u32 v91, v107, v91, s27
	v_lshl_add_u64 v[108:109], v[100:101], 0, s[28:29]
	v_pk_mul_f32 v[92:93], v[116:117], v[96:97] op_sel_hi:[0,1]
	v_and_or_b32 v96, v91, s30, v90
	v_bfe_u32 v90, v104, 16, 1
	v_add3_u32 v90, v104, v90, s27
	v_bfe_u32 v91, v105, 16, 1
	v_add_co_u32_e32 v114, vcc, s31, v108
	v_lshrrev_b32_e32 v90, 16, v90
	v_add3_u32 v91, v105, v91, s27
	v_addc_co_u32_e32 v115, vcc, 0, v109, vcc
	v_and_or_b32 v97, v91, s30, v90
	v_add_co_u32_e32 v90, vcc, s34, v108
	v_pk_mul_f32 v[92:93], v[4:5], v[92:93]
	s_nop 0
	v_addc_co_u32_e32 v91, vcc, 0, v109, vcc
	global_store_dwordx2 v[90:91], v[96:97], off offset:-4096
	v_bfe_u32 v96, v94, 16, 1
	v_add3_u32 v96, v94, v96, s27
	v_bfe_u32 v97, v95, 16, 1
	v_lshrrev_b32_e32 v96, 16, v96
	v_add3_u32 v97, v95, v97, s27
	v_and_or_b32 v96, v97, s30, v96
	v_bfe_u32 v97, v92, 16, 1
	v_add3_u32 v97, v92, v97, s27
	v_bfe_u32 v108, v93, 16, 1
	v_lshrrev_b32_e32 v97, 16, v97
	v_add3_u32 v108, v93, v108, s27
	v_and_or_b32 v97, v108, s30, v97
	v_pk_mul_f32 v[108:109], v[82:83], v[6:7]
	global_store_dwordx2 v[90:91], v[96:97], off
	v_pk_mul_f32 v[96:97], v[84:85], v[8:9]
	v_pk_mul_f32 v[84:85], v[116:117], v[86:87] op_sel_hi:[0,1]
	v_bfe_u32 v86, v108, 16, 1
	v_add3_u32 v86, v108, v86, s27
	v_bfe_u32 v87, v109, 16, 1
	v_lshrrev_b32_e32 v86, 16, v86
	v_add3_u32 v87, v109, v87, s27
	v_and_or_b32 v86, v87, s30, v86
	v_bfe_u32 v87, v96, 16, 1
	v_pk_mul_f32 v[82:83], v[116:117], v[88:89] op_sel_hi:[0,1]
	v_add3_u32 v87, v96, v87, s27
	v_bfe_u32 v88, v97, 16, 1
	v_lshrrev_b32_e32 v87, 16, v87
	v_add3_u32 v88, v97, v88, s27
	v_pk_mul_f32 v[84:85], v[6:7], v[84:85]
	v_and_or_b32 v87, v88, s30, v87
	global_store_dwordx2 v[114:115], v[86:87], off offset:512
	v_bfe_u32 v86, v84, 16, 1
	v_add3_u32 v86, v84, v86, s27
	v_bfe_u32 v87, v85, 16, 1
	v_pk_mul_f32 v[82:83], v[8:9], v[82:83]
	v_lshrrev_b32_e32 v86, 16, v86
	v_add3_u32 v87, v85, v87, s27
	v_and_or_b32 v86, v87, s30, v86
	v_bfe_u32 v87, v82, 16, 1
	v_add3_u32 v87, v82, v87, s27
	v_bfe_u32 v88, v83, 16, 1
	v_lshrrev_b32_e32 v87, 16, v87
	v_add3_u32 v88, v83, v88, s27
	v_and_or_b32 v87, v88, s30, v87
	global_store_dwordx2 v[90:91], v[86:87], off offset:512
	v_pk_mul_f32 v[86:87], v[74:75], v[10:11]
	v_pk_mul_f32 v[74:75], v[116:117], v[80:81] op_sel_hi:[0,1]
	v_bfe_u32 v80, v86, 16, 1
	v_add3_u32 v80, v86, v80, s27
	v_bfe_u32 v81, v87, 16, 1
	v_lshrrev_b32_e32 v80, 16, v80
	v_add3_u32 v81, v87, v81, s27
	v_and_or_b32 v80, v81, s30, v80
	v_bfe_u32 v81, v76, 16, 1
	v_add3_u32 v81, v76, v81, s27
	v_bfe_u32 v88, v77, 16, 1
	v_pk_mul_f32 v[78:79], v[116:117], v[78:79] op_sel_hi:[0,1]
	v_lshrrev_b32_e32 v81, 16, v81
	v_add3_u32 v88, v77, v88, s27
	v_pk_mul_f32 v[78:79], v[10:11], v[78:79]
	v_and_or_b32 v81, v88, s30, v81
	global_store_dwordx2 v[114:115], v[80:81], off offset:1024
	v_bfe_u32 v80, v78, 16, 1
	v_add3_u32 v80, v78, v80, s27
	v_bfe_u32 v81, v79, 16, 1
	v_pk_mul_f32 v[74:75], v[12:13], v[74:75]
	v_lshrrev_b32_e32 v80, 16, v80
	v_add3_u32 v81, v79, v81, s27
	v_and_or_b32 v80, v81, s30, v80
	v_bfe_u32 v81, v74, 16, 1
	v_add3_u32 v81, v74, v81, s27
	v_bfe_u32 v88, v75, 16, 1
	v_lshrrev_b32_e32 v81, 16, v81
	v_add3_u32 v88, v75, v88, s27
	v_pk_mul_f32 v[66:67], v[118:119], v[66:67] op_sel_hi:[0,1]
	v_and_or_b32 v81, v88, s30, v81
	v_pk_mul_f32 v[68:69], v[118:119], v[68:69] op_sel_hi:[0,1]
	v_pk_mul_f32 v[88:89], v[66:67], v[14:15]
	global_store_dwordx2 v[90:91], v[80:81], off offset:1024
	v_pk_mul_f32 v[80:81], v[68:69], v[16:17]
	v_pk_mul_f32 v[68:69], v[116:117], v[70:71] op_sel_hi:[0,1]
	v_bfe_u32 v70, v88, 16, 1
	v_add3_u32 v70, v88, v70, s27
	v_bfe_u32 v71, v89, 16, 1
	v_lshrrev_b32_e32 v70, 16, v70
	v_add3_u32 v71, v89, v71, s27
	v_and_or_b32 v70, v71, s30, v70
	v_bfe_u32 v71, v80, 16, 1
	v_pk_mul_f32 v[66:67], v[116:117], v[72:73] op_sel_hi:[0,1]
	v_add3_u32 v71, v80, v71, s27
	v_bfe_u32 v72, v81, 16, 1
	v_lshrrev_b32_e32 v71, 16, v71
	v_add3_u32 v72, v81, v72, s27
	v_pk_mul_f32 v[68:69], v[14:15], v[68:69]
	v_and_or_b32 v71, v72, s30, v71
	global_store_dwordx2 v[114:115], v[70:71], off offset:1536
	v_bfe_u32 v70, v68, 16, 1
	v_add3_u32 v70, v68, v70, s27
	v_bfe_u32 v71, v69, 16, 1
	v_pk_mul_f32 v[66:67], v[16:17], v[66:67]
	v_lshrrev_b32_e32 v70, 16, v70
	v_add3_u32 v71, v69, v71, s27
	v_and_or_b32 v70, v71, s30, v70
	v_bfe_u32 v71, v66, 16, 1
	v_add3_u32 v71, v66, v71, s27
	v_bfe_u32 v72, v67, 16, 1
	v_lshrrev_b32_e32 v71, 16, v71
	v_add3_u32 v72, v67, v72, s27
	v_and_or_b32 v71, v72, s30, v71
	v_pk_mul_f32 v[58:59], v[118:119], v[58:59] op_sel_hi:[0,1]
	global_store_dwordx2 v[90:91], v[70:71], off offset:1536
	v_pk_mul_f32 v[70:71], v[58:59], v[18:19]
	v_pk_mul_f32 v[58:59], v[116:117], v[64:65] op_sel_hi:[0,1]
	v_bfe_u32 v64, v70, 16, 1
	v_pk_mul_f32 v[60:61], v[118:119], v[60:61] op_sel_hi:[0,1]
	v_add3_u32 v64, v70, v64, s27
	v_bfe_u32 v65, v71, 16, 1
	v_pk_mul_f32 v[60:61], v[60:61], v[20:21]
	v_lshrrev_b32_e32 v64, 16, v64
	v_add3_u32 v65, v71, v65, s27
	v_and_or_b32 v64, v65, s30, v64
	v_bfe_u32 v65, v60, 16, 1
	v_add3_u32 v65, v60, v65, s27
	v_bfe_u32 v72, v61, 16, 1
	v_pk_mul_f32 v[62:63], v[116:117], v[62:63] op_sel_hi:[0,1]
	v_lshrrev_b32_e32 v65, 16, v65
	v_add3_u32 v72, v61, v72, s27
	v_pk_mul_f32 v[62:63], v[18:19], v[62:63]
	v_and_or_b32 v65, v72, s30, v65
	global_store_dwordx2 v[114:115], v[64:65], off offset:2048
	v_bfe_u32 v64, v62, 16, 1
	v_add3_u32 v64, v62, v64, s27
	v_bfe_u32 v65, v63, 16, 1
	v_pk_mul_f32 v[58:59], v[20:21], v[58:59]
	v_lshrrev_b32_e32 v64, 16, v64
	v_add3_u32 v65, v63, v65, s27
	v_and_or_b32 v64, v65, s30, v64
	v_bfe_u32 v65, v58, 16, 1
	v_add3_u32 v65, v58, v65, s27
	v_bfe_u32 v72, v59, 16, 1
	v_pk_mul_f32 v[54:55], v[118:119], v[54:55] op_sel_hi:[0,1]
	v_lshrrev_b32_e32 v65, 16, v65
	v_add3_u32 v72, v59, v72, s27
	v_pk_mul_f32 v[112:113], v[54:55], v[22:23]
	v_pk_mul_f32 v[50:51], v[116:117], v[50:51] op_sel_hi:[0,1]
	v_and_or_b32 v65, v72, s30, v65
	v_pk_mul_f32 v[72:73], v[22:23], v[50:51]
	v_bfe_u32 v50, v112, 16, 1
	v_pk_mul_f32 v[56:57], v[118:119], v[56:57] op_sel_hi:[0,1]
	v_add3_u32 v50, v112, v50, s27
	v_bfe_u32 v51, v113, 16, 1
	v_pk_mul_f32 v[110:111], v[56:57], v[24:25]
	v_lshrrev_b32_e32 v50, 16, v50
	v_add3_u32 v51, v113, v51, s27
	v_pk_mul_f32 v[52:53], v[116:117], v[52:53] op_sel_hi:[0,1]
	v_and_or_b32 v50, v51, s30, v50
	v_bfe_u32 v51, v110, 16, 1
	global_store_dwordx2 v[90:91], v[64:65], off offset:2048
	v_pk_mul_f32 v[64:65], v[24:25], v[52:53]
	v_add3_u32 v51, v110, v51, s27
	v_bfe_u32 v52, v111, 16, 1
	v_lshrrev_b32_e32 v51, 16, v51
	v_add3_u32 v52, v111, v52, s27
	v_and_or_b32 v51, v52, s30, v51
	global_store_dwordx2 v[114:115], v[50:51], off offset:2560
	v_bfe_u32 v50, v72, 16, 1
	v_add3_u32 v50, v72, v50, s27
	v_bfe_u32 v51, v73, 16, 1
	v_lshrrev_b32_e32 v50, 16, v50
	v_add3_u32 v51, v73, v51, s27
	v_and_or_b32 v50, v51, s30, v50
	v_bfe_u32 v51, v64, 16, 1
	v_add3_u32 v51, v64, v51, s27
	v_bfe_u32 v52, v65, 16, 1
	v_lshrrev_b32_e32 v51, 16, v51
	v_add3_u32 v52, v65, v52, s27
	v_and_or_b32 v51, v52, s30, v51
	global_store_dwordx2 v[90:91], v[50:51], off offset:2560
	v_pk_mul_f32 v[50:51], v[118:119], v[46:47] op_sel_hi:[0,1]
	v_pk_mul_f32 v[50:51], v[50:51], v[26:27]
	v_pk_mul_f32 v[42:43], v[116:117], v[42:43] op_sel_hi:[0,1]
	v_pk_mul_f32 v[46:47], v[118:119], v[48:49] op_sel_hi:[0,1]
	v_pk_mul_f32 v[48:49], v[26:27], v[42:43]
	v_bfe_u32 v42, v50, 16, 1
	v_add3_u32 v42, v50, v42, s27
	v_bfe_u32 v43, v51, 16, 1
	v_pk_mul_f32 v[46:47], v[46:47], v[28:29]
	v_lshrrev_b32_e32 v42, 16, v42
	v_add3_u32 v43, v51, v43, s27
	v_and_or_b32 v42, v43, s30, v42
	v_bfe_u32 v43, v46, 16, 1
	v_add3_u32 v43, v46, v43, s27
	v_bfe_u32 v52, v47, 16, 1
	v_lshrrev_b32_e32 v43, 16, v43
	v_add3_u32 v52, v47, v52, s27
	v_and_or_b32 v43, v52, s30, v43
	global_store_dwordx2 v[114:115], v[42:43], off offset:3072
	v_bfe_u32 v42, v48, 16, 1
	v_pk_mul_f32 v[44:45], v[116:117], v[44:45] op_sel_hi:[0,1]
	v_add3_u32 v42, v48, v42, s27
	v_bfe_u32 v43, v49, 16, 1
	v_pk_mul_f32 v[44:45], v[28:29], v[44:45]
	v_lshrrev_b32_e32 v42, 16, v42
	v_add3_u32 v43, v49, v43, s27
	v_pk_mul_f32 v[38:39], v[118:119], v[38:39] op_sel_hi:[0,1]
	v_and_or_b32 v42, v43, s30, v42
	v_bfe_u32 v43, v44, 16, 1
	v_pk_mul_f32 v[54:55], v[38:39], v[30:31]
	v_pk_mul_f32 v[34:35], v[116:117], v[34:35] op_sel_hi:[0,1]
	v_add3_u32 v43, v44, v43, s27
	v_bfe_u32 v52, v45, 16, 1
	v_pk_mul_f32 v[56:57], v[30:31], v[34:35]
	v_bfe_u32 v34, v54, 16, 1
	v_lshrrev_b32_e32 v43, 16, v43
	v_add3_u32 v52, v45, v52, s27
	v_pk_mul_f32 v[40:41], v[118:119], v[40:41] op_sel_hi:[0,1]
	v_add3_u32 v34, v54, v34, s27
	v_bfe_u32 v35, v55, 16, 1
	v_and_or_b32 v43, v52, s30, v43
	v_pk_mul_f32 v[52:53], v[40:41], v[32:33]
	v_lshrrev_b32_e32 v34, 16, v34
	v_add3_u32 v35, v55, v35, s27
	v_pk_mul_f32 v[36:37], v[116:117], v[36:37] op_sel_hi:[0,1]
	v_and_or_b32 v34, v35, s30, v34
	v_bfe_u32 v35, v52, 16, 1
	global_store_dwordx2 v[90:91], v[42:43], off offset:3072
	v_pk_mul_f32 v[42:43], v[32:33], v[36:37]
	v_add3_u32 v35, v52, v35, s27
	v_bfe_u32 v36, v53, 16, 1
	v_lshrrev_b32_e32 v35, 16, v35
	v_add3_u32 v36, v53, v36, s27
	v_and_or_b32 v35, v36, s30, v35
	global_store_dwordx2 v[114:115], v[34:35], off offset:3584
	v_bfe_u32 v34, v56, 16, 1
	v_add3_u32 v38, v56, v34, s27
	ds_read_b128 v[34:37], v1
	v_lshrrev_b32_e32 v114, 16, v38
	v_bfe_u32 v38, v57, 16, 1
	v_add3_u32 v115, v57, v38, s27
	ds_read_b128 v[38:41], v1 offset:1024
	s_waitcnt lgkmcnt(1)
	v_mul_f32_e32 v116, v35, v107
	v_mul_f32_e32 v35, v35, v95
	v_fmac_f32_e32 v116, v34, v106
	v_fmac_f32_e32 v35, v34, v94
	v_mul_f32_e32 v34, v37, v93
	v_mul_f32_e32 v118, v37, v105
	v_fmac_f32_e32 v34, v36, v92
	v_fmac_f32_e32 v118, v36, v104
	v_add_f32_e32 v34, v35, v34
	v_add_f32_e32 v116, v116, v118
	v_add_f32_e32 v118, 0, v34
	s_waitcnt lgkmcnt(0)
	v_mul_f32_e32 v34, v39, v109
	v_mul_f32_e32 v35, v41, v97
	v_fmac_f32_e32 v34, v38, v108
	v_fmac_f32_e32 v35, v40, v96
	v_add_f32_e32 v116, 0, v116
	v_add_f32_e32 v34, v34, v35
	v_add_f32_e32 v116, v116, v34
	v_mul_f32_e32 v39, v39, v85
	ds_read_b128 v[34:37], v1 offset:2048
	v_fmac_f32_e32 v39, v38, v84
	v_mul_f32_e32 v38, v41, v83
	v_fmac_f32_e32 v38, v40, v82
	v_add_f32_e32 v38, v39, v38
	v_add_f32_e32 v118, v118, v38
	ds_read_b128 v[38:41], v1 offset:3072
	s_waitcnt lgkmcnt(1)
	v_mul_f32_e32 v189, v35, v87
	v_mul_f32_e32 v35, v35, v79
	v_fmac_f32_e32 v189, v34, v86
	v_fmac_f32_e32 v35, v34, v78
	v_mul_f32_e32 v34, v37, v75
	v_fmac_f32_e32 v34, v36, v74
	v_mul_f32_e32 v190, v37, v77
	v_add_f32_e32 v34, v35, v34
	v_fmac_f32_e32 v190, v36, v76
	v_add_f32_e32 v118, v118, v34
	s_waitcnt lgkmcnt(0)
	v_mul_f32_e32 v34, v39, v89
	v_mul_f32_e32 v35, v41, v81
	v_add_f32_e32 v189, v189, v190
	v_fmac_f32_e32 v34, v38, v88
	v_fmac_f32_e32 v35, v40, v80
	v_add_f32_e32 v116, v116, v189
	v_add_f32_e32 v34, v34, v35
	v_add_f32_e32 v116, v116, v34
	v_mul_f32_e32 v39, v39, v69
	ds_read_b128 v[34:37], v1 offset:4096
	v_fmac_f32_e32 v39, v38, v68
	v_mul_f32_e32 v38, v41, v67
	v_fmac_f32_e32 v38, v40, v66
	v_add_f32_e32 v38, v39, v38
	v_add_f32_e32 v118, v118, v38
	ds_read_b128 v[38:41], v1 offset:5120
	s_waitcnt lgkmcnt(1)
	v_mul_f32_e32 v189, v35, v71
	v_mul_f32_e32 v35, v35, v63
	v_fmac_f32_e32 v189, v34, v70
	v_fmac_f32_e32 v35, v34, v62
	v_mul_f32_e32 v34, v37, v59
	v_fmac_f32_e32 v34, v36, v58
	v_mul_f32_e32 v190, v37, v61
	v_add_f32_e32 v34, v35, v34
	v_fmac_f32_e32 v190, v36, v60
	v_add_f32_e32 v118, v118, v34
	s_waitcnt lgkmcnt(0)
	v_mul_f32_e32 v34, v39, v113
	v_mul_f32_e32 v35, v41, v111
	v_add_f32_e32 v189, v189, v190
	v_fmac_f32_e32 v34, v38, v112
	v_fmac_f32_e32 v35, v40, v110
	v_add_f32_e32 v116, v116, v189
	v_add_f32_e32 v34, v34, v35
	v_add_f32_e32 v116, v116, v34
	v_mul_f32_e32 v39, v39, v73
	ds_read_b128 v[34:37], v1 offset:6144
	v_fmac_f32_e32 v39, v38, v72
	v_mul_f32_e32 v38, v41, v65
	v_fmac_f32_e32 v38, v40, v64
	v_add_f32_e32 v38, v39, v38
	v_add_f32_e32 v118, v118, v38
	ds_read_b128 v[38:41], v1 offset:7168
	s_waitcnt lgkmcnt(1)
	v_mul_f32_e32 v189, v35, v51
	v_mul_f32_e32 v35, v35, v49
	v_fmac_f32_e32 v189, v34, v50
	v_fmac_f32_e32 v35, v34, v48
	v_mul_f32_e32 v34, v37, v45
	v_fmac_f32_e32 v34, v36, v44
	v_mul_f32_e32 v190, v37, v47
	v_add_f32_e32 v34, v35, v34
	v_fmac_f32_e32 v190, v36, v46
	v_add_f32_e32 v118, v118, v34
	s_waitcnt lgkmcnt(0)
	v_mul_f32_e32 v34, v39, v55
	v_mul_f32_e32 v35, v41, v53
	v_add_f32_e32 v189, v189, v190
	v_fmac_f32_e32 v34, v38, v54
	v_fmac_f32_e32 v35, v40, v52
	v_add_f32_e32 v116, v116, v189
	v_add_f32_e32 v34, v34, v35
	v_add_f32_e32 v116, v116, v34
	v_mul_f32_e32 v39, v39, v57
	ds_read_b128 v[34:37], v1 offset:8192
	v_fmac_f32_e32 v39, v38, v56
	v_mul_f32_e32 v38, v41, v43
	v_fmac_f32_e32 v38, v40, v42
	v_add_f32_e32 v38, v39, v38
	v_add_f32_e32 v118, v118, v38
	ds_read_b128 v[38:41], v1 offset:9216
	s_waitcnt lgkmcnt(1)
	v_mul_f32_e32 v189, v35, v107
	v_mul_f32_e32 v35, v35, v95
	v_fmac_f32_e32 v189, v34, v106
	v_fmac_f32_e32 v35, v34, v94
	v_mul_f32_e32 v34, v37, v93
	v_mul_f32_e32 v190, v37, v105
	v_fmac_f32_e32 v34, v36, v92
	v_fmac_f32_e32 v190, v36, v104
	v_add_f32_e32 v34, v35, v34
	v_add_f32_e32 v189, v189, v190
	v_add_f32_e32 v190, 0, v34
	s_waitcnt lgkmcnt(0)
	v_mul_f32_e32 v34, v39, v109
	v_mul_f32_e32 v35, v41, v97
	v_fmac_f32_e32 v34, v38, v108
	v_fmac_f32_e32 v35, v40, v96
	v_add_f32_e32 v189, 0, v189
	v_add_f32_e32 v34, v34, v35
	v_add_f32_e32 v189, v189, v34
	v_mul_f32_e32 v39, v39, v85
	ds_read_b128 v[34:37], v1 offset:10240
	v_fmac_f32_e32 v39, v38, v84
	v_mul_f32_e32 v38, v41, v83
	v_fmac_f32_e32 v38, v40, v82
	v_add_f32_e32 v38, v39, v38
	v_add_f32_e32 v190, v190, v38
	ds_read_b128 v[38:41], v1 offset:11264
	s_waitcnt lgkmcnt(1)
	v_mul_f32_e32 v191, v35, v87
	v_mul_f32_e32 v35, v35, v79
	v_fmac_f32_e32 v191, v34, v86
	v_fmac_f32_e32 v35, v34, v78
	v_mul_f32_e32 v34, v37, v75
	v_fmac_f32_e32 v34, v36, v74
	v_mul_f32_e32 v192, v37, v77
	v_add_f32_e32 v34, v35, v34
	v_fmac_f32_e32 v192, v36, v76
	v_add_f32_e32 v190, v190, v34
	s_waitcnt lgkmcnt(0)
	v_mul_f32_e32 v34, v39, v89
	v_mul_f32_e32 v35, v41, v81
	v_add_f32_e32 v191, v191, v192
	v_fmac_f32_e32 v34, v38, v88
	v_fmac_f32_e32 v35, v40, v80
	v_add_f32_e32 v189, v189, v191
	v_add_f32_e32 v34, v34, v35
	v_add_f32_e32 v189, v189, v34
	v_mul_f32_e32 v39, v39, v69
	ds_read_b128 v[34:37], v1 offset:12288
	v_fmac_f32_e32 v39, v38, v68
	v_mul_f32_e32 v38, v41, v67
	v_fmac_f32_e32 v38, v40, v66
	v_add_f32_e32 v38, v39, v38
	v_add_f32_e32 v190, v190, v38
	ds_read_b128 v[38:41], v1 offset:13312
	s_waitcnt lgkmcnt(1)
	v_mul_f32_e32 v191, v35, v71
	v_mul_f32_e32 v35, v35, v63
	v_fmac_f32_e32 v191, v34, v70
	v_fmac_f32_e32 v35, v34, v62
	v_mul_f32_e32 v34, v37, v59
	v_fmac_f32_e32 v34, v36, v58
	v_mul_f32_e32 v192, v37, v61
	v_add_f32_e32 v34, v35, v34
	v_fmac_f32_e32 v192, v36, v60
	v_add_f32_e32 v190, v190, v34
	s_waitcnt lgkmcnt(0)
	v_mul_f32_e32 v34, v39, v113
	v_mul_f32_e32 v35, v41, v111
	v_add_f32_e32 v191, v191, v192
	v_fmac_f32_e32 v34, v38, v112
	v_fmac_f32_e32 v35, v40, v110
	v_add_f32_e32 v189, v189, v191
	v_add_f32_e32 v34, v34, v35
	v_add_f32_e32 v189, v189, v34
	v_mul_f32_e32 v39, v39, v73
	ds_read_b128 v[34:37], v1 offset:14336
	v_fmac_f32_e32 v39, v38, v72
	v_mul_f32_e32 v38, v41, v65
	v_fmac_f32_e32 v38, v40, v64
	v_add_f32_e32 v38, v39, v38
	v_add_f32_e32 v190, v190, v38
	ds_read_b128 v[38:41], v1 offset:15360
	s_waitcnt lgkmcnt(1)
	v_mul_f32_e32 v191, v35, v51
	v_mul_f32_e32 v35, v35, v49
	v_fmac_f32_e32 v191, v34, v50
	v_fmac_f32_e32 v35, v34, v48
	v_mul_f32_e32 v34, v37, v45
	v_fmac_f32_e32 v34, v36, v44
	v_mul_f32_e32 v192, v37, v47
	v_add_f32_e32 v34, v35, v34
	v_fmac_f32_e32 v192, v36, v46
	v_add_f32_e32 v190, v190, v34
	s_waitcnt lgkmcnt(0)
	v_mul_f32_e32 v34, v39, v55
	v_mul_f32_e32 v35, v41, v53
	v_add_f32_e32 v191, v191, v192
	v_fmac_f32_e32 v34, v38, v54
	v_fmac_f32_e32 v35, v40, v52
	v_add_f32_e32 v189, v189, v191
	v_add_f32_e32 v34, v34, v35
	v_add_f32_e32 v189, v189, v34
	v_mul_f32_e32 v39, v39, v57
	ds_read_b128 v[34:37], v1 offset:16384
	v_fmac_f32_e32 v39, v38, v56
	v_mul_f32_e32 v38, v41, v43
	v_fmac_f32_e32 v38, v40, v42
	v_add_f32_e32 v38, v39, v38
	v_add_f32_e32 v190, v190, v38
	ds_read_b128 v[38:41], v1 offset:17408
	s_waitcnt lgkmcnt(1)
	v_mul_f32_e32 v191, v35, v107
	v_mul_f32_e32 v35, v35, v95
	v_fmac_f32_e32 v191, v34, v106
	v_fmac_f32_e32 v35, v34, v94
	v_mul_f32_e32 v34, v37, v93
	v_mul_f32_e32 v192, v37, v105
	v_fmac_f32_e32 v34, v36, v92
	v_fmac_f32_e32 v192, v36, v104
	v_add_f32_e32 v34, v35, v34
	v_add_f32_e32 v191, v191, v192
	v_add_f32_e32 v192, 0, v34
	s_waitcnt lgkmcnt(0)
	v_mul_f32_e32 v34, v39, v109
	v_mul_f32_e32 v35, v41, v97
	v_fmac_f32_e32 v34, v38, v108
	v_fmac_f32_e32 v35, v40, v96
	v_add_f32_e32 v191, 0, v191
	v_add_f32_e32 v34, v34, v35
	v_add_f32_e32 v191, v191, v34
	v_mul_f32_e32 v39, v39, v85
	ds_read_b128 v[34:37], v1 offset:18432
	v_fmac_f32_e32 v39, v38, v84
	v_mul_f32_e32 v38, v41, v83
	v_fmac_f32_e32 v38, v40, v82
	v_add_f32_e32 v38, v39, v38
	v_add_f32_e32 v192, v192, v38
	ds_read_b128 v[38:41], v1 offset:19456
	s_waitcnt lgkmcnt(1)
	v_mul_f32_e32 v193, v35, v87
	v_mul_f32_e32 v35, v35, v79
	v_fmac_f32_e32 v193, v34, v86
	v_fmac_f32_e32 v35, v34, v78
	v_mul_f32_e32 v34, v37, v75
	v_fmac_f32_e32 v34, v36, v74
	v_mul_f32_e32 v194, v37, v77
	v_add_f32_e32 v34, v35, v34
	v_fmac_f32_e32 v194, v36, v76
	v_add_f32_e32 v192, v192, v34
	s_waitcnt lgkmcnt(0)
	v_mul_f32_e32 v34, v39, v89
	v_mul_f32_e32 v35, v41, v81
	v_add_f32_e32 v193, v193, v194
	v_fmac_f32_e32 v34, v38, v88
	v_fmac_f32_e32 v35, v40, v80
	v_add_f32_e32 v191, v191, v193
	v_add_f32_e32 v34, v34, v35
	v_add_f32_e32 v191, v191, v34
	v_mul_f32_e32 v39, v39, v69
	ds_read_b128 v[34:37], v1 offset:20480
	v_fmac_f32_e32 v39, v38, v68
	v_mul_f32_e32 v38, v41, v67
	v_fmac_f32_e32 v38, v40, v66
	v_add_f32_e32 v38, v39, v38
	v_add_f32_e32 v192, v192, v38
	ds_read_b128 v[38:41], v1 offset:21504
	s_waitcnt lgkmcnt(1)
	v_mul_f32_e32 v193, v35, v71
	v_mul_f32_e32 v35, v35, v63
	v_fmac_f32_e32 v193, v34, v70
	v_fmac_f32_e32 v35, v34, v62
	v_mul_f32_e32 v34, v37, v59
	v_fmac_f32_e32 v34, v36, v58
	v_mul_f32_e32 v194, v37, v61
	v_add_f32_e32 v34, v35, v34
	v_fmac_f32_e32 v194, v36, v60
	v_add_f32_e32 v192, v192, v34
	s_waitcnt lgkmcnt(0)
	v_mul_f32_e32 v34, v39, v113
	v_mul_f32_e32 v35, v41, v111
	v_add_f32_e32 v193, v193, v194
	v_fmac_f32_e32 v34, v38, v112
	v_fmac_f32_e32 v35, v40, v110
	v_add_f32_e32 v191, v191, v193
	v_add_f32_e32 v34, v34, v35
	v_add_f32_e32 v191, v191, v34
	v_mul_f32_e32 v39, v39, v73
	ds_read_b128 v[34:37], v1 offset:22528
	v_fmac_f32_e32 v39, v38, v72
	v_mul_f32_e32 v38, v41, v65
	v_fmac_f32_e32 v38, v40, v64
	v_add_f32_e32 v38, v39, v38
	v_add_f32_e32 v192, v192, v38
	ds_read_b128 v[38:41], v1 offset:23552
	s_waitcnt lgkmcnt(1)
	v_mul_f32_e32 v193, v35, v51
	v_mul_f32_e32 v35, v35, v49
	v_fmac_f32_e32 v193, v34, v50
	v_fmac_f32_e32 v35, v34, v48
	v_mul_f32_e32 v34, v37, v45
	v_fmac_f32_e32 v34, v36, v44
	v_mul_f32_e32 v194, v37, v47
	v_add_f32_e32 v34, v35, v34
	v_fmac_f32_e32 v194, v36, v46
	v_add_f32_e32 v192, v192, v34
	s_waitcnt lgkmcnt(0)
	v_mul_f32_e32 v34, v39, v55
	v_mul_f32_e32 v35, v41, v53
	v_add_f32_e32 v193, v193, v194
	v_fmac_f32_e32 v34, v38, v54
	v_fmac_f32_e32 v35, v40, v52
	v_add_f32_e32 v191, v191, v193
	v_add_f32_e32 v34, v34, v35
	v_add_f32_e32 v191, v191, v34
	v_mul_f32_e32 v39, v39, v57
	ds_read_b128 v[34:37], v1 offset:24576
	v_fmac_f32_e32 v39, v38, v56
	v_mul_f32_e32 v38, v41, v43
	v_fmac_f32_e32 v38, v40, v42
	v_add_f32_e32 v38, v39, v38
	v_add_f32_e32 v192, v192, v38
	ds_read_b128 v[38:41], v1 offset:25600
	s_waitcnt lgkmcnt(1)
	v_mul_f32_e32 v193, v35, v107
	v_mul_f32_e32 v35, v35, v95
	v_fmac_f32_e32 v193, v34, v106
	v_fmac_f32_e32 v35, v34, v94
	v_mul_f32_e32 v34, v37, v93
	v_mul_f32_e32 v194, v37, v105
	v_fmac_f32_e32 v34, v36, v92
	v_fmac_f32_e32 v194, v36, v104
	v_add_f32_e32 v34, v35, v34
	v_add_f32_e32 v193, v193, v194
	v_add_f32_e32 v194, 0, v34
	s_waitcnt lgkmcnt(0)
	v_mul_f32_e32 v34, v39, v109
	v_mul_f32_e32 v35, v41, v97
	v_fmac_f32_e32 v34, v38, v108
	v_fmac_f32_e32 v35, v40, v96
	v_add_f32_e32 v193, 0, v193
	v_add_f32_e32 v34, v34, v35
	v_add_f32_e32 v193, v193, v34
	v_mul_f32_e32 v39, v39, v85
	ds_read_b128 v[34:37], v1 offset:26624
	v_fmac_f32_e32 v39, v38, v84
	v_mul_f32_e32 v38, v41, v83
	v_fmac_f32_e32 v38, v40, v82
	v_add_f32_e32 v38, v39, v38
	v_add_f32_e32 v194, v194, v38
	ds_read_b128 v[38:41], v1 offset:27648
	s_waitcnt lgkmcnt(1)
	v_mul_f32_e32 v195, v35, v87
	v_mul_f32_e32 v35, v35, v79
	v_fmac_f32_e32 v195, v34, v86
	v_fmac_f32_e32 v35, v34, v78
	v_mul_f32_e32 v34, v37, v75
	v_fmac_f32_e32 v34, v36, v74
	v_mul_f32_e32 v196, v37, v77
	v_add_f32_e32 v34, v35, v34
	v_fmac_f32_e32 v196, v36, v76
	v_add_f32_e32 v194, v194, v34
	s_waitcnt lgkmcnt(0)
	v_mul_f32_e32 v34, v39, v89
	v_mul_f32_e32 v35, v41, v81
	v_add_f32_e32 v195, v195, v196
	v_fmac_f32_e32 v34, v38, v88
	v_fmac_f32_e32 v35, v40, v80
	v_add_f32_e32 v193, v193, v195
	v_add_f32_e32 v34, v34, v35
	v_add_f32_e32 v193, v193, v34
	v_mul_f32_e32 v39, v39, v69
	ds_read_b128 v[34:37], v1 offset:28672
	v_fmac_f32_e32 v39, v38, v68
	v_mul_f32_e32 v38, v41, v67
	v_fmac_f32_e32 v38, v40, v66
	v_add_f32_e32 v38, v39, v38
	v_add_f32_e32 v194, v194, v38
	ds_read_b128 v[38:41], v1 offset:29696
	s_waitcnt lgkmcnt(1)
	v_mul_f32_e32 v195, v35, v71
	v_mul_f32_e32 v35, v35, v63
	v_fmac_f32_e32 v195, v34, v70
	v_fmac_f32_e32 v35, v34, v62
	v_mul_f32_e32 v34, v37, v59
	v_fmac_f32_e32 v34, v36, v58
	v_mul_f32_e32 v196, v37, v61
	v_add_f32_e32 v34, v35, v34
	v_fmac_f32_e32 v196, v36, v60
	v_add_f32_e32 v194, v194, v34
	s_waitcnt lgkmcnt(0)
	v_mul_f32_e32 v34, v39, v113
	v_mul_f32_e32 v35, v41, v111
	v_add_f32_e32 v195, v195, v196
	v_fmac_f32_e32 v34, v38, v112
	v_fmac_f32_e32 v35, v40, v110
	v_add_f32_e32 v193, v193, v195
	v_add_f32_e32 v34, v34, v35
	v_add_f32_e32 v193, v193, v34
	v_mul_f32_e32 v39, v39, v73
	ds_read_b128 v[34:37], v1 offset:30720
	v_fmac_f32_e32 v39, v38, v72
	v_mul_f32_e32 v38, v41, v65
	v_fmac_f32_e32 v38, v40, v64
	v_add_f32_e32 v38, v39, v38
	v_add_f32_e32 v194, v194, v38
	ds_read_b128 v[38:41], v1 offset:31744
	s_waitcnt lgkmcnt(1)
	v_mul_f32_e32 v195, v35, v51
	v_mul_f32_e32 v35, v35, v49
	v_fmac_f32_e32 v195, v34, v50
	v_fmac_f32_e32 v35, v34, v48
	v_mul_f32_e32 v34, v37, v45
	v_fmac_f32_e32 v34, v36, v44
	v_mul_f32_e32 v196, v37, v47
	v_add_f32_e32 v34, v35, v34
	v_fmac_f32_e32 v196, v36, v46
	v_add_f32_e32 v194, v194, v34
	s_waitcnt lgkmcnt(0)
	v_mul_f32_e32 v34, v39, v55
	v_mul_f32_e32 v35, v41, v53
	v_add_f32_e32 v195, v195, v196
	v_fmac_f32_e32 v34, v38, v54
	v_fmac_f32_e32 v35, v40, v52
	v_add_f32_e32 v193, v193, v195
	v_add_f32_e32 v34, v34, v35
	v_add_f32_e32 v193, v193, v34
	v_mul_f32_e32 v39, v39, v57
	ds_read_b128 v[34:37], v1 offset:32768
	v_fmac_f32_e32 v39, v38, v56
	v_mul_f32_e32 v38, v41, v43
	v_fmac_f32_e32 v38, v40, v42
	v_add_f32_e32 v38, v39, v38
	v_add_f32_e32 v194, v194, v38
	ds_read_b128 v[38:41], v1 offset:33792
	s_waitcnt lgkmcnt(1)
	v_mul_f32_e32 v195, v35, v107
	v_mul_f32_e32 v35, v35, v95
	v_fmac_f32_e32 v195, v34, v106
	v_fmac_f32_e32 v35, v34, v94
	v_mul_f32_e32 v34, v37, v93
	v_mul_f32_e32 v196, v37, v105
	v_fmac_f32_e32 v34, v36, v92
	v_fmac_f32_e32 v196, v36, v104
	v_add_f32_e32 v34, v35, v34
	v_add_f32_e32 v195, v195, v196
	v_add_f32_e32 v196, 0, v34
	s_waitcnt lgkmcnt(0)
	v_mul_f32_e32 v34, v39, v109
	v_mul_f32_e32 v35, v41, v97
	v_fmac_f32_e32 v34, v38, v108
	v_fmac_f32_e32 v35, v40, v96
	v_add_f32_e32 v195, 0, v195
	v_add_f32_e32 v34, v34, v35
	v_add_f32_e32 v195, v195, v34
	v_mul_f32_e32 v39, v39, v85
	ds_read_b128 v[34:37], v1 offset:34816
	v_fmac_f32_e32 v39, v38, v84
	v_mul_f32_e32 v38, v41, v83
	v_fmac_f32_e32 v38, v40, v82
	v_add_f32_e32 v38, v39, v38
	v_add_f32_e32 v196, v196, v38
	ds_read_b128 v[38:41], v1 offset:35840
	s_waitcnt lgkmcnt(1)
	v_mul_f32_e32 v197, v35, v87
	v_mul_f32_e32 v35, v35, v79
	v_fmac_f32_e32 v197, v34, v86
	v_fmac_f32_e32 v35, v34, v78
	v_mul_f32_e32 v34, v37, v75
	v_fmac_f32_e32 v34, v36, v74
	v_mul_f32_e32 v198, v37, v77
	v_add_f32_e32 v34, v35, v34
	v_fmac_f32_e32 v198, v36, v76
	v_add_f32_e32 v196, v196, v34
	s_waitcnt lgkmcnt(0)
	v_mul_f32_e32 v34, v39, v89
	v_mul_f32_e32 v35, v41, v81
	v_add_f32_e32 v197, v197, v198
	v_fmac_f32_e32 v34, v38, v88
	v_fmac_f32_e32 v35, v40, v80
	v_add_f32_e32 v195, v195, v197
	v_add_f32_e32 v34, v34, v35
	v_add_f32_e32 v195, v195, v34
	v_mul_f32_e32 v39, v39, v69
	ds_read_b128 v[34:37], v1 offset:36864
	v_fmac_f32_e32 v39, v38, v68
	v_mul_f32_e32 v38, v41, v67
	v_fmac_f32_e32 v38, v40, v66
	v_add_f32_e32 v38, v39, v38
	v_add_f32_e32 v196, v196, v38
	ds_read_b128 v[38:41], v1 offset:37888
	s_waitcnt lgkmcnt(1)
	v_mul_f32_e32 v197, v35, v71
	v_mul_f32_e32 v35, v35, v63
	v_fmac_f32_e32 v197, v34, v70
	v_fmac_f32_e32 v35, v34, v62
	v_mul_f32_e32 v34, v37, v59
	v_fmac_f32_e32 v34, v36, v58
	v_mul_f32_e32 v198, v37, v61
	v_add_f32_e32 v34, v35, v34
	v_fmac_f32_e32 v198, v36, v60
	v_add_f32_e32 v196, v196, v34
	s_waitcnt lgkmcnt(0)
	v_mul_f32_e32 v34, v39, v113
	v_mul_f32_e32 v35, v41, v111
	v_add_f32_e32 v197, v197, v198
	v_fmac_f32_e32 v34, v38, v112
	v_fmac_f32_e32 v35, v40, v110
	v_add_f32_e32 v195, v195, v197
	v_add_f32_e32 v34, v34, v35
	v_add_f32_e32 v195, v195, v34
	v_mul_f32_e32 v39, v39, v73
	ds_read_b128 v[34:37], v1 offset:38912
	v_fmac_f32_e32 v39, v38, v72
	v_mul_f32_e32 v38, v41, v65
	v_fmac_f32_e32 v38, v40, v64
	v_add_f32_e32 v38, v39, v38
	v_add_f32_e32 v196, v196, v38
	ds_read_b128 v[38:41], v1 offset:39936
	s_waitcnt lgkmcnt(1)
	v_mul_f32_e32 v197, v35, v51
	v_mul_f32_e32 v35, v35, v49
	v_fmac_f32_e32 v197, v34, v50
	v_fmac_f32_e32 v35, v34, v48
	v_mul_f32_e32 v34, v37, v45
	v_fmac_f32_e32 v34, v36, v44
	v_mul_f32_e32 v198, v37, v47
	v_add_f32_e32 v34, v35, v34
	v_fmac_f32_e32 v198, v36, v46
	v_add_f32_e32 v196, v196, v34
	s_waitcnt lgkmcnt(0)
	v_mul_f32_e32 v34, v39, v55
	v_mul_f32_e32 v35, v41, v53
	v_add_f32_e32 v197, v197, v198
	v_fmac_f32_e32 v34, v38, v54
	v_fmac_f32_e32 v35, v40, v52
	v_add_f32_e32 v195, v195, v197
	v_add_f32_e32 v34, v34, v35
	v_add_f32_e32 v195, v195, v34
	v_mul_f32_e32 v39, v39, v57
	ds_read_b128 v[34:37], v1 offset:40960
	v_fmac_f32_e32 v39, v38, v56
	v_mul_f32_e32 v38, v41, v43
	v_fmac_f32_e32 v38, v40, v42
	v_add_f32_e32 v38, v39, v38
	v_add_f32_e32 v196, v196, v38
	ds_read_b128 v[38:41], v1 offset:41984
	s_waitcnt lgkmcnt(1)
	v_mul_f32_e32 v197, v35, v107
	v_mul_f32_e32 v35, v35, v95
	v_fmac_f32_e32 v197, v34, v106
	v_fmac_f32_e32 v35, v34, v94
	v_mul_f32_e32 v34, v37, v93
	v_mul_f32_e32 v198, v37, v105
	v_fmac_f32_e32 v34, v36, v92
	v_fmac_f32_e32 v198, v36, v104
	v_add_f32_e32 v34, v35, v34
	v_add_f32_e32 v197, v197, v198
	v_add_f32_e32 v198, 0, v34
	s_waitcnt lgkmcnt(0)
	v_mul_f32_e32 v34, v39, v109
	v_mul_f32_e32 v35, v41, v97
	v_fmac_f32_e32 v34, v38, v108
	v_fmac_f32_e32 v35, v40, v96
	v_add_f32_e32 v197, 0, v197
	v_add_f32_e32 v34, v34, v35
	v_add_f32_e32 v197, v197, v34
	v_mul_f32_e32 v39, v39, v85
	ds_read_b128 v[34:37], v1 offset:43008
	v_fmac_f32_e32 v39, v38, v84
	v_mul_f32_e32 v38, v41, v83
	v_fmac_f32_e32 v38, v40, v82
	v_add_f32_e32 v38, v39, v38
	v_add_f32_e32 v198, v198, v38
	ds_read_b128 v[38:41], v1 offset:44032
	s_waitcnt lgkmcnt(1)
	v_mul_f32_e32 v199, v35, v87
	v_mul_f32_e32 v35, v35, v79
	v_fmac_f32_e32 v199, v34, v86
	v_fmac_f32_e32 v35, v34, v78
	v_mul_f32_e32 v34, v37, v75
	v_fmac_f32_e32 v34, v36, v74
	v_mul_f32_e32 v200, v37, v77
	v_add_f32_e32 v34, v35, v34
	v_fmac_f32_e32 v200, v36, v76
	v_add_f32_e32 v198, v198, v34
	s_waitcnt lgkmcnt(0)
	v_mul_f32_e32 v34, v39, v89
	v_mul_f32_e32 v35, v41, v81
	v_add_f32_e32 v199, v199, v200
	v_fmac_f32_e32 v34, v38, v88
	v_fmac_f32_e32 v35, v40, v80
	v_add_f32_e32 v197, v197, v199
	v_add_f32_e32 v34, v34, v35
	v_add_f32_e32 v197, v197, v34
	v_mul_f32_e32 v39, v39, v69
	ds_read_b128 v[34:37], v1 offset:45056
	v_fmac_f32_e32 v39, v38, v68
	v_mul_f32_e32 v38, v41, v67
	v_fmac_f32_e32 v38, v40, v66
	v_add_f32_e32 v38, v39, v38
	v_add_f32_e32 v198, v198, v38
	ds_read_b128 v[38:41], v1 offset:46080
	s_waitcnt lgkmcnt(1)
	v_mul_f32_e32 v199, v35, v71
	v_mul_f32_e32 v35, v35, v63
	v_fmac_f32_e32 v199, v34, v70
	v_fmac_f32_e32 v35, v34, v62
	v_mul_f32_e32 v34, v37, v59
	v_fmac_f32_e32 v34, v36, v58
	v_mul_f32_e32 v200, v37, v61
	v_add_f32_e32 v34, v35, v34
	v_fmac_f32_e32 v200, v36, v60
	v_add_f32_e32 v198, v198, v34
	s_waitcnt lgkmcnt(0)
	v_mul_f32_e32 v34, v39, v113
	v_mul_f32_e32 v35, v41, v111
	v_add_f32_e32 v199, v199, v200
	v_fmac_f32_e32 v34, v38, v112
	v_fmac_f32_e32 v35, v40, v110
	v_add_f32_e32 v197, v197, v199
	v_add_f32_e32 v34, v34, v35
	v_add_f32_e32 v197, v197, v34
	v_mul_f32_e32 v39, v39, v73
	ds_read_b128 v[34:37], v1 offset:47104
	v_fmac_f32_e32 v39, v38, v72
	v_mul_f32_e32 v38, v41, v65
	v_fmac_f32_e32 v38, v40, v64
	v_add_f32_e32 v38, v39, v38
	v_add_f32_e32 v198, v198, v38
	ds_read_b128 v[38:41], v1 offset:48128
	s_waitcnt lgkmcnt(1)
	v_mul_f32_e32 v199, v35, v51
	v_mul_f32_e32 v35, v35, v49
	v_fmac_f32_e32 v199, v34, v50
	v_fmac_f32_e32 v35, v34, v48
	v_mul_f32_e32 v34, v37, v45
	v_fmac_f32_e32 v34, v36, v44
	v_mul_f32_e32 v200, v37, v47
	v_add_f32_e32 v34, v35, v34
	v_fmac_f32_e32 v200, v36, v46
	v_add_f32_e32 v198, v198, v34
	s_waitcnt lgkmcnt(0)
	v_mul_f32_e32 v34, v39, v55
	v_mul_f32_e32 v35, v41, v53
	v_add_f32_e32 v199, v199, v200
	v_fmac_f32_e32 v34, v38, v54
	v_fmac_f32_e32 v35, v40, v52
	v_add_f32_e32 v197, v197, v199
	v_add_f32_e32 v34, v34, v35
	v_add_f32_e32 v197, v197, v34
	v_mul_f32_e32 v39, v39, v57
	ds_read_b128 v[34:37], v1 offset:49152
	v_fmac_f32_e32 v39, v38, v56
	v_mul_f32_e32 v38, v41, v43
	v_fmac_f32_e32 v38, v40, v42
	v_add_f32_e32 v38, v39, v38
	v_add_f32_e32 v198, v198, v38
	ds_read_b128 v[38:41], v1 offset:50176
	s_waitcnt lgkmcnt(1)
	v_mul_f32_e32 v199, v35, v107
	v_mul_f32_e32 v35, v35, v95
	v_fmac_f32_e32 v199, v34, v106
	v_fmac_f32_e32 v35, v34, v94
	v_mul_f32_e32 v34, v37, v93
	v_mul_f32_e32 v200, v37, v105
	v_fmac_f32_e32 v34, v36, v92
	v_fmac_f32_e32 v200, v36, v104
	v_add_f32_e32 v34, v35, v34
	v_add_f32_e32 v199, v199, v200
	v_add_f32_e32 v200, 0, v34
	s_waitcnt lgkmcnt(0)
	v_mul_f32_e32 v34, v39, v109
	v_mul_f32_e32 v35, v41, v97
	v_fmac_f32_e32 v34, v38, v108
	v_fmac_f32_e32 v35, v40, v96
	v_add_f32_e32 v199, 0, v199
	v_add_f32_e32 v34, v34, v35
	v_add_f32_e32 v199, v199, v34
	v_mul_f32_e32 v39, v39, v85
	ds_read_b128 v[34:37], v1 offset:51200
	v_fmac_f32_e32 v39, v38, v84
	v_mul_f32_e32 v38, v41, v83
	v_fmac_f32_e32 v38, v40, v82
	v_add_f32_e32 v38, v39, v38
	v_add_f32_e32 v200, v200, v38
	ds_read_b128 v[38:41], v1 offset:52224
	s_waitcnt lgkmcnt(1)
	v_mul_f32_e32 v201, v35, v87
	v_mul_f32_e32 v35, v35, v79
	v_fmac_f32_e32 v201, v34, v86
	v_fmac_f32_e32 v35, v34, v78
	v_mul_f32_e32 v34, v37, v75
	v_fmac_f32_e32 v34, v36, v74
	v_mul_f32_e32 v202, v37, v77
	v_add_f32_e32 v34, v35, v34
	v_fmac_f32_e32 v202, v36, v76
	v_add_f32_e32 v200, v200, v34
	s_waitcnt lgkmcnt(0)
	v_mul_f32_e32 v34, v39, v89
	v_mul_f32_e32 v35, v41, v81
	v_add_f32_e32 v201, v201, v202
	v_fmac_f32_e32 v34, v38, v88
	v_fmac_f32_e32 v35, v40, v80
	v_add_f32_e32 v199, v199, v201
	v_add_f32_e32 v34, v34, v35
	v_add_f32_e32 v199, v199, v34
	v_mul_f32_e32 v39, v39, v69
	ds_read_b128 v[34:37], v1 offset:53248
	v_fmac_f32_e32 v39, v38, v68
	v_mul_f32_e32 v38, v41, v67
	v_fmac_f32_e32 v38, v40, v66
	v_add_f32_e32 v38, v39, v38
	v_add_f32_e32 v200, v200, v38
	ds_read_b128 v[38:41], v1 offset:54272
	s_waitcnt lgkmcnt(1)
	v_mul_f32_e32 v201, v35, v71
	v_mul_f32_e32 v35, v35, v63
	v_fmac_f32_e32 v201, v34, v70
	v_fmac_f32_e32 v35, v34, v62
	v_mul_f32_e32 v34, v37, v59
	v_fmac_f32_e32 v34, v36, v58
	v_mul_f32_e32 v202, v37, v61
	v_add_f32_e32 v34, v35, v34
	v_fmac_f32_e32 v202, v36, v60
	v_add_f32_e32 v200, v200, v34
	s_waitcnt lgkmcnt(0)
	v_mul_f32_e32 v34, v39, v113
	v_mul_f32_e32 v35, v41, v111
	v_add_f32_e32 v201, v201, v202
	v_fmac_f32_e32 v34, v38, v112
	v_fmac_f32_e32 v35, v40, v110
	v_add_f32_e32 v199, v199, v201
	v_add_f32_e32 v34, v34, v35
	v_add_f32_e32 v199, v199, v34
	v_mul_f32_e32 v39, v39, v73
	ds_read_b128 v[34:37], v1 offset:55296
	v_fmac_f32_e32 v39, v38, v72
	v_mul_f32_e32 v38, v41, v65
	v_fmac_f32_e32 v38, v40, v64
	v_add_f32_e32 v38, v39, v38
	v_add_f32_e32 v200, v200, v38
	ds_read_b128 v[38:41], v1 offset:56320
	s_waitcnt lgkmcnt(1)
	v_mul_f32_e32 v201, v35, v51
	v_mul_f32_e32 v35, v35, v49
	v_fmac_f32_e32 v201, v34, v50
	v_fmac_f32_e32 v35, v34, v48
	v_mul_f32_e32 v34, v37, v45
	v_fmac_f32_e32 v34, v36, v44
	v_mul_f32_e32 v202, v37, v47
	v_add_f32_e32 v34, v35, v34
	v_fmac_f32_e32 v202, v36, v46
	v_add_f32_e32 v200, v200, v34
	s_waitcnt lgkmcnt(0)
	v_mul_f32_e32 v34, v39, v55
	v_mul_f32_e32 v35, v41, v53
	v_add_f32_e32 v201, v201, v202
	v_fmac_f32_e32 v34, v38, v54
	v_fmac_f32_e32 v35, v40, v52
	v_add_f32_e32 v199, v199, v201
	v_add_f32_e32 v34, v34, v35
	v_add_f32_e32 v199, v199, v34
	v_mul_f32_e32 v39, v39, v57
	ds_read_b128 v[34:37], v1 offset:57344
	v_fmac_f32_e32 v39, v38, v56
	v_mul_f32_e32 v38, v41, v43
	v_fmac_f32_e32 v38, v40, v42
	v_add_f32_e32 v38, v39, v38
	v_add_f32_e32 v200, v200, v38
	ds_read_b128 v[38:41], v1 offset:58368
	s_waitcnt lgkmcnt(1)
	v_mul_f32_e32 v201, v35, v107
	v_mul_f32_e32 v35, v35, v95
	v_fmac_f32_e32 v201, v34, v106
	v_fmac_f32_e32 v35, v34, v94
	v_mul_f32_e32 v34, v37, v93
	v_mul_f32_e32 v202, v37, v105
	v_fmac_f32_e32 v34, v36, v92
	v_fmac_f32_e32 v202, v36, v104
	v_add_f32_e32 v34, v35, v34
	v_add_f32_e32 v201, v201, v202
	v_add_f32_e32 v202, 0, v34
	s_waitcnt lgkmcnt(0)
	v_mul_f32_e32 v34, v39, v109
	v_mul_f32_e32 v35, v41, v97
	v_fmac_f32_e32 v34, v38, v108
	v_fmac_f32_e32 v35, v40, v96
	v_add_f32_e32 v201, 0, v201
	v_add_f32_e32 v34, v34, v35
	v_add_f32_e32 v201, v201, v34
	v_mul_f32_e32 v39, v39, v85
	ds_read_b128 v[34:37], v1 offset:59392
	v_fmac_f32_e32 v39, v38, v84
	v_mul_f32_e32 v38, v41, v83
	v_fmac_f32_e32 v38, v40, v82
	v_add_f32_e32 v38, v39, v38
	v_add_f32_e32 v202, v202, v38
	ds_read_b128 v[38:41], v1 offset:60416
	s_waitcnt lgkmcnt(1)
	v_mul_f32_e32 v203, v35, v87
	v_mul_f32_e32 v35, v35, v79
	v_fmac_f32_e32 v203, v34, v86
	v_fmac_f32_e32 v35, v34, v78
	v_mul_f32_e32 v34, v37, v75
	v_fmac_f32_e32 v34, v36, v74
	v_mul_f32_e32 v204, v37, v77
	v_add_f32_e32 v34, v35, v34
	v_fmac_f32_e32 v204, v36, v76
	v_add_f32_e32 v202, v202, v34
	s_waitcnt lgkmcnt(0)
	v_mul_f32_e32 v34, v39, v89
	v_mul_f32_e32 v35, v41, v81
	v_add_f32_e32 v203, v203, v204
	v_fmac_f32_e32 v34, v38, v88
	v_fmac_f32_e32 v35, v40, v80
	v_add_f32_e32 v201, v201, v203
	v_add_f32_e32 v34, v34, v35
	v_add_f32_e32 v201, v201, v34
	v_mul_f32_e32 v39, v39, v69
	ds_read_b128 v[34:37], v1 offset:61440
	v_fmac_f32_e32 v39, v38, v68
	v_mul_f32_e32 v38, v41, v67
	v_fmac_f32_e32 v38, v40, v66
	v_add_f32_e32 v38, v39, v38
	v_add_f32_e32 v202, v202, v38
	ds_read_b128 v[38:41], v1 offset:62464
	s_waitcnt lgkmcnt(1)
	v_mul_f32_e32 v203, v35, v71
	v_mul_f32_e32 v35, v35, v63
	v_fmac_f32_e32 v203, v34, v70
	v_fmac_f32_e32 v35, v34, v62
	v_mul_f32_e32 v34, v37, v59
	v_fmac_f32_e32 v34, v36, v58
	v_mul_f32_e32 v204, v37, v61
	v_add_f32_e32 v34, v35, v34
	v_fmac_f32_e32 v204, v36, v60
	v_add_f32_e32 v202, v202, v34
	s_waitcnt lgkmcnt(0)
	v_mul_f32_e32 v34, v39, v113
	v_mul_f32_e32 v35, v41, v111
	v_add_f32_e32 v203, v203, v204
	v_fmac_f32_e32 v34, v38, v112
	v_fmac_f32_e32 v35, v40, v110
	v_add_f32_e32 v201, v201, v203
	v_add_f32_e32 v34, v34, v35
	v_add_f32_e32 v201, v201, v34
	v_mul_f32_e32 v39, v39, v73
	ds_read_b128 v[34:37], v1 offset:63488
	v_fmac_f32_e32 v39, v38, v72
	v_mul_f32_e32 v38, v41, v65
	v_fmac_f32_e32 v38, v40, v64
	v_add_f32_e32 v38, v39, v38
	v_add_f32_e32 v202, v202, v38
	ds_read_b128 v[38:41], v1 offset:64512
	s_waitcnt lgkmcnt(1)
	v_mul_f32_e32 v203, v35, v51
	v_mul_f32_e32 v35, v35, v49
	v_fmac_f32_e32 v203, v34, v50
	v_fmac_f32_e32 v35, v34, v48
	v_mul_f32_e32 v34, v37, v45
	v_fmac_f32_e32 v34, v36, v44
	v_mul_f32_e32 v204, v37, v47
	v_add_f32_e32 v34, v35, v34
	v_fmac_f32_e32 v204, v36, v46
	v_add_f32_e32 v202, v202, v34
	s_waitcnt lgkmcnt(0)
	v_mul_f32_e32 v34, v39, v55
	v_mul_f32_e32 v35, v41, v53
	v_add_f32_e32 v203, v203, v204
	v_fmac_f32_e32 v34, v38, v54
	v_fmac_f32_e32 v35, v40, v52
	v_add_f32_e32 v201, v201, v203
	v_add_f32_e32 v34, v34, v35
	v_add_f32_e32 v201, v201, v34
	v_mul_f32_e32 v39, v39, v57
	ds_read_b128 v[34:37], v119
	v_fmac_f32_e32 v39, v38, v56
	v_mul_f32_e32 v38, v41, v43
	v_fmac_f32_e32 v38, v40, v42
	v_add_f32_e32 v38, v39, v38
	v_add_f32_e32 v202, v202, v38
	ds_read_b128 v[38:41], v120
	s_waitcnt lgkmcnt(1)
	v_mul_f32_e32 v203, v35, v107
	v_mul_f32_e32 v35, v35, v95
	v_fmac_f32_e32 v203, v34, v106
	v_fmac_f32_e32 v35, v34, v94
	v_mul_f32_e32 v34, v37, v93
	v_mul_f32_e32 v204, v37, v105
	v_fmac_f32_e32 v34, v36, v92
	v_fmac_f32_e32 v204, v36, v104
	v_add_f32_e32 v34, v35, v34
	v_add_f32_e32 v203, v203, v204
	v_add_f32_e32 v204, 0, v34
	s_waitcnt lgkmcnt(0)
	v_mul_f32_e32 v34, v39, v109
	v_mul_f32_e32 v35, v41, v97
	v_fmac_f32_e32 v34, v38, v108
	v_fmac_f32_e32 v35, v40, v96
	v_add_f32_e32 v203, 0, v203
	v_add_f32_e32 v34, v34, v35
	v_add_f32_e32 v203, v203, v34
	v_mul_f32_e32 v39, v39, v85
	ds_read_b128 v[34:37], v121
	v_fmac_f32_e32 v39, v38, v84
	v_mul_f32_e32 v38, v41, v83
	v_fmac_f32_e32 v38, v40, v82
	v_add_f32_e32 v38, v39, v38
	v_add_f32_e32 v204, v204, v38
	ds_read_b128 v[38:41], v122
	s_waitcnt lgkmcnt(1)
	v_mul_f32_e32 v205, v35, v87
	v_mul_f32_e32 v35, v35, v79
	v_fmac_f32_e32 v205, v34, v86
	v_fmac_f32_e32 v35, v34, v78
	v_mul_f32_e32 v34, v37, v75
	v_fmac_f32_e32 v34, v36, v74
	v_mul_f32_e32 v206, v37, v77
	v_add_f32_e32 v34, v35, v34
	v_fmac_f32_e32 v206, v36, v76
	v_add_f32_e32 v204, v204, v34
	s_waitcnt lgkmcnt(0)
	v_mul_f32_e32 v34, v39, v89
	v_mul_f32_e32 v35, v41, v81
	v_add_f32_e32 v205, v205, v206
	v_fmac_f32_e32 v34, v38, v88
	v_fmac_f32_e32 v35, v40, v80
	v_add_f32_e32 v203, v203, v205
	v_add_f32_e32 v34, v34, v35
	v_add_f32_e32 v203, v203, v34
	v_mul_f32_e32 v39, v39, v69
	ds_read_b128 v[34:37], v123
	v_fmac_f32_e32 v39, v38, v68
	v_mul_f32_e32 v38, v41, v67
	v_fmac_f32_e32 v38, v40, v66
	v_add_f32_e32 v38, v39, v38
	v_add_f32_e32 v204, v204, v38
	ds_read_b128 v[38:41], v124
	s_waitcnt lgkmcnt(1)
	v_mul_f32_e32 v205, v35, v71
	v_mul_f32_e32 v35, v35, v63
	v_fmac_f32_e32 v205, v34, v70
	v_fmac_f32_e32 v35, v34, v62
	v_mul_f32_e32 v34, v37, v59
	v_fmac_f32_e32 v34, v36, v58
	v_mul_f32_e32 v206, v37, v61
	v_add_f32_e32 v34, v35, v34
	v_fmac_f32_e32 v206, v36, v60
	v_add_f32_e32 v204, v204, v34
	s_waitcnt lgkmcnt(0)
	v_mul_f32_e32 v34, v39, v113
	v_mul_f32_e32 v35, v41, v111
	v_add_f32_e32 v205, v205, v206
	v_fmac_f32_e32 v34, v38, v112
	v_fmac_f32_e32 v35, v40, v110
	v_add_f32_e32 v203, v203, v205
	v_add_f32_e32 v34, v34, v35
	v_add_f32_e32 v203, v203, v34
	v_mul_f32_e32 v39, v39, v73
	ds_read_b128 v[34:37], v125
	v_fmac_f32_e32 v39, v38, v72
	v_mul_f32_e32 v38, v41, v65
	v_fmac_f32_e32 v38, v40, v64
	v_add_f32_e32 v38, v39, v38
	v_add_f32_e32 v204, v204, v38
	ds_read_b128 v[38:41], v126
	s_waitcnt lgkmcnt(1)
	v_mul_f32_e32 v205, v35, v51
	v_mul_f32_e32 v35, v35, v49
	v_fmac_f32_e32 v205, v34, v50
	v_fmac_f32_e32 v35, v34, v48
	v_mul_f32_e32 v34, v37, v45
	v_fmac_f32_e32 v34, v36, v44
	v_mul_f32_e32 v206, v37, v47
	v_add_f32_e32 v34, v35, v34
	v_fmac_f32_e32 v206, v36, v46
	v_add_f32_e32 v204, v204, v34
	s_waitcnt lgkmcnt(0)
	v_mul_f32_e32 v34, v39, v55
	v_mul_f32_e32 v35, v41, v53
	v_add_f32_e32 v205, v205, v206
	v_fmac_f32_e32 v34, v38, v54
	v_fmac_f32_e32 v35, v40, v52
	v_add_f32_e32 v203, v203, v205
	v_add_f32_e32 v34, v34, v35
	v_add_f32_e32 v203, v203, v34
	v_mul_f32_e32 v39, v39, v57
	ds_read_b128 v[34:37], v127
	v_fmac_f32_e32 v39, v38, v56
	v_mul_f32_e32 v38, v41, v43
	v_fmac_f32_e32 v38, v40, v42
	v_add_f32_e32 v38, v39, v38
	v_add_f32_e32 v204, v204, v38
	ds_read_b128 v[38:41], v128
	s_waitcnt lgkmcnt(1)
	v_mul_f32_e32 v205, v35, v107
	v_mul_f32_e32 v35, v35, v95
	v_fmac_f32_e32 v205, v34, v106
	v_fmac_f32_e32 v35, v34, v94
	v_mul_f32_e32 v34, v37, v93
	v_mul_f32_e32 v206, v37, v105
	v_fmac_f32_e32 v34, v36, v92
	v_fmac_f32_e32 v206, v36, v104
	v_add_f32_e32 v34, v35, v34
	v_add_f32_e32 v205, v205, v206
	v_add_f32_e32 v206, 0, v34
	s_waitcnt lgkmcnt(0)
	v_mul_f32_e32 v34, v39, v109
	v_mul_f32_e32 v35, v41, v97
	v_fmac_f32_e32 v34, v38, v108
	v_fmac_f32_e32 v35, v40, v96
	v_add_f32_e32 v205, 0, v205
	v_add_f32_e32 v34, v34, v35
	v_add_f32_e32 v205, v205, v34
	v_mul_f32_e32 v39, v39, v85
	ds_read_b128 v[34:37], v129
	v_fmac_f32_e32 v39, v38, v84
	v_mul_f32_e32 v38, v41, v83
	v_fmac_f32_e32 v38, v40, v82
	v_add_f32_e32 v38, v39, v38
	v_add_f32_e32 v206, v206, v38
	ds_read_b128 v[38:41], v130
	s_waitcnt lgkmcnt(1)
	v_mul_f32_e32 v207, v35, v87
	v_mul_f32_e32 v35, v35, v79
	v_fmac_f32_e32 v207, v34, v86
	v_fmac_f32_e32 v35, v34, v78
	v_mul_f32_e32 v34, v37, v75
	v_fmac_f32_e32 v34, v36, v74
	v_mul_f32_e32 v208, v37, v77
	v_add_f32_e32 v34, v35, v34
	v_fmac_f32_e32 v208, v36, v76
	v_add_f32_e32 v206, v206, v34
	s_waitcnt lgkmcnt(0)
	v_mul_f32_e32 v34, v39, v89
	v_mul_f32_e32 v35, v41, v81
	v_add_f32_e32 v207, v207, v208
	v_fmac_f32_e32 v34, v38, v88
	v_fmac_f32_e32 v35, v40, v80
	v_add_f32_e32 v205, v205, v207
	v_add_f32_e32 v34, v34, v35
	v_add_f32_e32 v205, v205, v34
	v_mul_f32_e32 v39, v39, v69
	ds_read_b128 v[34:37], v131
	v_fmac_f32_e32 v39, v38, v68
	v_mul_f32_e32 v38, v41, v67
	v_fmac_f32_e32 v38, v40, v66
	v_add_f32_e32 v38, v39, v38
	v_add_f32_e32 v206, v206, v38
	ds_read_b128 v[38:41], v132
	s_waitcnt lgkmcnt(1)
	v_mul_f32_e32 v207, v35, v71
	v_mul_f32_e32 v35, v35, v63
	v_fmac_f32_e32 v207, v34, v70
	v_fmac_f32_e32 v35, v34, v62
	v_mul_f32_e32 v34, v37, v59
	v_fmac_f32_e32 v34, v36, v58
	v_mul_f32_e32 v208, v37, v61
	v_add_f32_e32 v34, v35, v34
	v_fmac_f32_e32 v208, v36, v60
	v_add_f32_e32 v206, v206, v34
	s_waitcnt lgkmcnt(0)
	v_mul_f32_e32 v34, v39, v113
	v_mul_f32_e32 v35, v41, v111
	v_add_f32_e32 v207, v207, v208
	v_fmac_f32_e32 v34, v38, v112
	v_fmac_f32_e32 v35, v40, v110
	v_add_f32_e32 v205, v205, v207
	v_add_f32_e32 v34, v34, v35
	v_add_f32_e32 v205, v205, v34
	v_mul_f32_e32 v39, v39, v73
	ds_read_b128 v[34:37], v133
	v_fmac_f32_e32 v39, v38, v72
	v_mul_f32_e32 v38, v41, v65
	v_fmac_f32_e32 v38, v40, v64
	v_add_f32_e32 v38, v39, v38
	v_add_f32_e32 v206, v206, v38
	ds_read_b128 v[38:41], v134
	s_waitcnt lgkmcnt(1)
	v_mul_f32_e32 v207, v35, v51
	v_mul_f32_e32 v35, v35, v49
	v_fmac_f32_e32 v207, v34, v50
	v_fmac_f32_e32 v35, v34, v48
	v_mul_f32_e32 v34, v37, v45
	v_fmac_f32_e32 v34, v36, v44
	v_mul_f32_e32 v208, v37, v47
	v_add_f32_e32 v34, v35, v34
	v_fmac_f32_e32 v208, v36, v46
	v_add_f32_e32 v206, v206, v34
	s_waitcnt lgkmcnt(0)
	v_mul_f32_e32 v34, v39, v55
	v_mul_f32_e32 v35, v41, v53
	v_add_f32_e32 v207, v207, v208
	v_fmac_f32_e32 v34, v38, v54
	v_fmac_f32_e32 v35, v40, v52
	v_add_f32_e32 v205, v205, v207
	v_add_f32_e32 v34, v34, v35
	v_add_f32_e32 v205, v205, v34
	v_mul_f32_e32 v39, v39, v57
	ds_read_b128 v[34:37], v135
	v_fmac_f32_e32 v39, v38, v56
	v_mul_f32_e32 v38, v41, v43
	v_fmac_f32_e32 v38, v40, v42
	v_add_f32_e32 v38, v39, v38
	v_add_f32_e32 v206, v206, v38
	ds_read_b128 v[38:41], v136
	s_waitcnt lgkmcnt(1)
	v_mul_f32_e32 v207, v35, v107
	v_mul_f32_e32 v35, v35, v95
	v_fmac_f32_e32 v207, v34, v106
	v_fmac_f32_e32 v35, v34, v94
	v_mul_f32_e32 v34, v37, v93
	v_mul_f32_e32 v208, v37, v105
	v_fmac_f32_e32 v34, v36, v92
	v_fmac_f32_e32 v208, v36, v104
	v_add_f32_e32 v34, v35, v34
	v_add_f32_e32 v207, v207, v208
	v_add_f32_e32 v208, 0, v34
	s_waitcnt lgkmcnt(0)
	v_mul_f32_e32 v34, v39, v109
	v_mul_f32_e32 v35, v41, v97
	v_fmac_f32_e32 v34, v38, v108
	v_fmac_f32_e32 v35, v40, v96
	v_add_f32_e32 v207, 0, v207
	v_add_f32_e32 v34, v34, v35
	v_add_f32_e32 v207, v207, v34
	v_mul_f32_e32 v39, v39, v85
	ds_read_b128 v[34:37], v137
	v_fmac_f32_e32 v39, v38, v84
	v_mul_f32_e32 v38, v41, v83
	v_fmac_f32_e32 v38, v40, v82
	v_add_f32_e32 v38, v39, v38
	v_add_f32_e32 v208, v208, v38
	ds_read_b128 v[38:41], v138
	s_waitcnt lgkmcnt(1)
	v_mul_f32_e32 v209, v35, v87
	v_mul_f32_e32 v35, v35, v79
	v_fmac_f32_e32 v209, v34, v86
	v_fmac_f32_e32 v35, v34, v78
	v_mul_f32_e32 v34, v37, v75
	v_fmac_f32_e32 v34, v36, v74
	v_mul_f32_e32 v210, v37, v77
	v_add_f32_e32 v34, v35, v34
	v_fmac_f32_e32 v210, v36, v76
	v_add_f32_e32 v208, v208, v34
	s_waitcnt lgkmcnt(0)
	v_mul_f32_e32 v34, v39, v89
	v_mul_f32_e32 v35, v41, v81
	v_add_f32_e32 v209, v209, v210
	v_fmac_f32_e32 v34, v38, v88
	v_fmac_f32_e32 v35, v40, v80
	v_add_f32_e32 v207, v207, v209
	v_add_f32_e32 v34, v34, v35
	v_add_f32_e32 v207, v207, v34
	v_mul_f32_e32 v39, v39, v69
	ds_read_b128 v[34:37], v139
	v_fmac_f32_e32 v39, v38, v68
	v_mul_f32_e32 v38, v41, v67
	v_fmac_f32_e32 v38, v40, v66
	v_add_f32_e32 v38, v39, v38
	v_add_f32_e32 v208, v208, v38
	ds_read_b128 v[38:41], v140
	s_waitcnt lgkmcnt(1)
	v_mul_f32_e32 v209, v35, v71
	v_mul_f32_e32 v35, v35, v63
	v_fmac_f32_e32 v209, v34, v70
	v_fmac_f32_e32 v35, v34, v62
	v_mul_f32_e32 v34, v37, v59
	v_fmac_f32_e32 v34, v36, v58
	v_mul_f32_e32 v210, v37, v61
	v_add_f32_e32 v34, v35, v34
	v_fmac_f32_e32 v210, v36, v60
	v_add_f32_e32 v208, v208, v34
	s_waitcnt lgkmcnt(0)
	v_mul_f32_e32 v34, v39, v113
	v_mul_f32_e32 v35, v41, v111
	v_add_f32_e32 v209, v209, v210
	v_fmac_f32_e32 v34, v38, v112
	v_fmac_f32_e32 v35, v40, v110
	v_add_f32_e32 v207, v207, v209
	v_add_f32_e32 v34, v34, v35
	v_add_f32_e32 v207, v207, v34
	v_mul_f32_e32 v39, v39, v73
	ds_read_b128 v[34:37], v141
	v_fmac_f32_e32 v39, v38, v72
	v_mul_f32_e32 v38, v41, v65
	v_fmac_f32_e32 v38, v40, v64
	v_add_f32_e32 v38, v39, v38
	v_add_f32_e32 v208, v208, v38
	ds_read_b128 v[38:41], v142
	s_waitcnt lgkmcnt(1)
	v_mul_f32_e32 v209, v35, v51
	v_mul_f32_e32 v35, v35, v49
	v_fmac_f32_e32 v209, v34, v50
	v_fmac_f32_e32 v35, v34, v48
	v_mul_f32_e32 v34, v37, v45
	v_fmac_f32_e32 v34, v36, v44
	v_mul_f32_e32 v210, v37, v47
	v_add_f32_e32 v34, v35, v34
	v_fmac_f32_e32 v210, v36, v46
	v_add_f32_e32 v208, v208, v34
	s_waitcnt lgkmcnt(0)
	v_mul_f32_e32 v34, v39, v55
	v_mul_f32_e32 v35, v41, v53
	v_add_f32_e32 v209, v209, v210
	v_fmac_f32_e32 v34, v38, v54
	v_fmac_f32_e32 v35, v40, v52
	v_add_f32_e32 v207, v207, v209
	v_add_f32_e32 v34, v34, v35
	v_add_f32_e32 v207, v207, v34
	v_mul_f32_e32 v39, v39, v57
	ds_read_b128 v[34:37], v143
	v_fmac_f32_e32 v39, v38, v56
	v_mul_f32_e32 v38, v41, v43
	v_fmac_f32_e32 v38, v40, v42
	v_add_f32_e32 v38, v39, v38
	v_add_f32_e32 v208, v208, v38
	ds_read_b128 v[38:41], v144
	s_waitcnt lgkmcnt(1)
	v_mul_f32_e32 v209, v35, v107
	v_mul_f32_e32 v35, v35, v95
	v_fmac_f32_e32 v209, v34, v106
	v_fmac_f32_e32 v35, v34, v94
	v_mul_f32_e32 v34, v37, v93
	v_mul_f32_e32 v210, v37, v105
	v_fmac_f32_e32 v34, v36, v92
	v_fmac_f32_e32 v210, v36, v104
	v_add_f32_e32 v34, v35, v34
	v_add_f32_e32 v209, v209, v210
	v_add_f32_e32 v210, 0, v34
	s_waitcnt lgkmcnt(0)
	v_mul_f32_e32 v34, v39, v109
	v_mul_f32_e32 v35, v41, v97
	v_fmac_f32_e32 v34, v38, v108
	v_fmac_f32_e32 v35, v40, v96
	v_add_f32_e32 v209, 0, v209
	v_add_f32_e32 v34, v34, v35
	v_add_f32_e32 v209, v209, v34
	v_mul_f32_e32 v39, v39, v85
	ds_read_b128 v[34:37], v145
	v_fmac_f32_e32 v39, v38, v84
	v_mul_f32_e32 v38, v41, v83
	v_fmac_f32_e32 v38, v40, v82
	v_add_f32_e32 v38, v39, v38
	v_add_f32_e32 v210, v210, v38
	ds_read_b128 v[38:41], v146
	s_waitcnt lgkmcnt(1)
	v_mul_f32_e32 v211, v35, v87
	v_mul_f32_e32 v35, v35, v79
	v_fmac_f32_e32 v211, v34, v86
	v_fmac_f32_e32 v35, v34, v78
	v_mul_f32_e32 v34, v37, v75
	v_fmac_f32_e32 v34, v36, v74
	v_mul_f32_e32 v212, v37, v77
	v_add_f32_e32 v34, v35, v34
	v_fmac_f32_e32 v212, v36, v76
	v_add_f32_e32 v210, v210, v34
	s_waitcnt lgkmcnt(0)
	v_mul_f32_e32 v34, v39, v89
	v_mul_f32_e32 v35, v41, v81
	v_add_f32_e32 v211, v211, v212
	v_fmac_f32_e32 v34, v38, v88
	v_fmac_f32_e32 v35, v40, v80
	v_add_f32_e32 v209, v209, v211
	v_add_f32_e32 v34, v34, v35
	v_add_f32_e32 v209, v209, v34
	v_mul_f32_e32 v39, v39, v69
	ds_read_b128 v[34:37], v147
	v_fmac_f32_e32 v39, v38, v68
	v_mul_f32_e32 v38, v41, v67
	v_fmac_f32_e32 v38, v40, v66
	v_add_f32_e32 v38, v39, v38
	v_add_f32_e32 v210, v210, v38
	ds_read_b128 v[38:41], v148
	s_waitcnt lgkmcnt(1)
	v_mul_f32_e32 v211, v35, v71
	v_mul_f32_e32 v35, v35, v63
	v_fmac_f32_e32 v211, v34, v70
	v_fmac_f32_e32 v35, v34, v62
	v_mul_f32_e32 v34, v37, v59
	v_fmac_f32_e32 v34, v36, v58
	v_mul_f32_e32 v212, v37, v61
	v_add_f32_e32 v34, v35, v34
	v_fmac_f32_e32 v212, v36, v60
	v_add_f32_e32 v210, v210, v34
	s_waitcnt lgkmcnt(0)
	v_mul_f32_e32 v34, v39, v113
	v_mul_f32_e32 v35, v41, v111
	v_add_f32_e32 v211, v211, v212
	v_fmac_f32_e32 v34, v38, v112
	v_fmac_f32_e32 v35, v40, v110
	v_add_f32_e32 v209, v209, v211
	v_add_f32_e32 v34, v34, v35
	v_add_f32_e32 v209, v209, v34
	v_mul_f32_e32 v39, v39, v73
	ds_read_b128 v[34:37], v149
	v_fmac_f32_e32 v39, v38, v72
	v_mul_f32_e32 v38, v41, v65
	v_fmac_f32_e32 v38, v40, v64
	v_add_f32_e32 v38, v39, v38
	v_add_f32_e32 v210, v210, v38
	ds_read_b128 v[38:41], v150
	s_waitcnt lgkmcnt(1)
	v_mul_f32_e32 v211, v35, v51
	v_mul_f32_e32 v35, v35, v49
	v_fmac_f32_e32 v211, v34, v50
	v_fmac_f32_e32 v35, v34, v48
	v_mul_f32_e32 v34, v37, v45
	v_fmac_f32_e32 v34, v36, v44
	v_mul_f32_e32 v212, v37, v47
	v_add_f32_e32 v34, v35, v34
	v_fmac_f32_e32 v212, v36, v46
	v_add_f32_e32 v210, v210, v34
	s_waitcnt lgkmcnt(0)
	v_mul_f32_e32 v34, v39, v55
	v_mul_f32_e32 v35, v41, v53
	v_add_f32_e32 v211, v211, v212
	v_fmac_f32_e32 v34, v38, v54
	v_fmac_f32_e32 v35, v40, v52
	v_add_f32_e32 v209, v209, v211
	v_add_f32_e32 v34, v34, v35
	v_add_f32_e32 v209, v209, v34
	v_mul_f32_e32 v39, v39, v57
	ds_read_b128 v[34:37], v151
	v_fmac_f32_e32 v39, v38, v56
	v_mul_f32_e32 v38, v41, v43
	v_fmac_f32_e32 v38, v40, v42
	v_add_f32_e32 v38, v39, v38
	v_add_f32_e32 v210, v210, v38
	ds_read_b128 v[38:41], v152
	s_waitcnt lgkmcnt(1)
	v_mul_f32_e32 v211, v35, v107
	v_mul_f32_e32 v35, v35, v95
	v_fmac_f32_e32 v211, v34, v106
	v_fmac_f32_e32 v35, v34, v94
	v_mul_f32_e32 v34, v37, v93
	v_mul_f32_e32 v212, v37, v105
	v_fmac_f32_e32 v34, v36, v92
	v_fmac_f32_e32 v212, v36, v104
	v_add_f32_e32 v34, v35, v34
	v_add_f32_e32 v211, v211, v212
	v_add_f32_e32 v212, 0, v34
	s_waitcnt lgkmcnt(0)
	v_mul_f32_e32 v34, v39, v109
	v_mul_f32_e32 v35, v41, v97
	v_fmac_f32_e32 v34, v38, v108
	v_fmac_f32_e32 v35, v40, v96
	v_add_f32_e32 v211, 0, v211
	v_add_f32_e32 v34, v34, v35
	v_add_f32_e32 v211, v211, v34
	v_mul_f32_e32 v39, v39, v85
	ds_read_b128 v[34:37], v153
	v_fmac_f32_e32 v39, v38, v84
	v_mul_f32_e32 v38, v41, v83
	v_fmac_f32_e32 v38, v40, v82
	v_add_f32_e32 v38, v39, v38
	v_add_f32_e32 v212, v212, v38
	ds_read_b128 v[38:41], v154
	s_waitcnt lgkmcnt(1)
	v_mul_f32_e32 v213, v35, v87
	v_mul_f32_e32 v35, v35, v79
	v_fmac_f32_e32 v213, v34, v86
	v_fmac_f32_e32 v35, v34, v78
	v_mul_f32_e32 v34, v37, v75
	v_fmac_f32_e32 v34, v36, v74
	v_mul_f32_e32 v214, v37, v77
	v_add_f32_e32 v34, v35, v34
	v_fmac_f32_e32 v214, v36, v76
	v_add_f32_e32 v212, v212, v34
	s_waitcnt lgkmcnt(0)
	v_mul_f32_e32 v34, v39, v89
	v_mul_f32_e32 v35, v41, v81
	v_add_f32_e32 v213, v213, v214
	v_fmac_f32_e32 v34, v38, v88
	v_fmac_f32_e32 v35, v40, v80
	v_add_f32_e32 v211, v211, v213
	v_add_f32_e32 v34, v34, v35
	v_add_f32_e32 v211, v211, v34
	v_mul_f32_e32 v39, v39, v69
	ds_read_b128 v[34:37], v155
	v_fmac_f32_e32 v39, v38, v68
	v_mul_f32_e32 v38, v41, v67
	v_fmac_f32_e32 v38, v40, v66
	v_add_f32_e32 v38, v39, v38
	v_add_f32_e32 v212, v212, v38
	ds_read_b128 v[38:41], v156
	s_waitcnt lgkmcnt(1)
	v_mul_f32_e32 v213, v35, v71
	v_mul_f32_e32 v35, v35, v63
	v_fmac_f32_e32 v213, v34, v70
	v_fmac_f32_e32 v35, v34, v62
	v_mul_f32_e32 v34, v37, v59
	v_fmac_f32_e32 v34, v36, v58
	v_mul_f32_e32 v214, v37, v61
	v_add_f32_e32 v34, v35, v34
	v_fmac_f32_e32 v214, v36, v60
	v_add_f32_e32 v212, v212, v34
	s_waitcnt lgkmcnt(0)
	v_mul_f32_e32 v34, v39, v113
	v_mul_f32_e32 v35, v41, v111
	v_add_f32_e32 v213, v213, v214
	v_fmac_f32_e32 v34, v38, v112
	v_fmac_f32_e32 v35, v40, v110
	v_add_f32_e32 v211, v211, v213
	v_add_f32_e32 v34, v34, v35
	v_add_f32_e32 v211, v211, v34
	v_mul_f32_e32 v39, v39, v73
	ds_read_b128 v[34:37], v157
	v_fmac_f32_e32 v39, v38, v72
	v_mul_f32_e32 v38, v41, v65
	v_fmac_f32_e32 v38, v40, v64
	v_add_f32_e32 v38, v39, v38
	v_add_f32_e32 v212, v212, v38
	ds_read_b128 v[38:41], v158
	s_waitcnt lgkmcnt(1)
	v_mul_f32_e32 v213, v35, v51
	v_mul_f32_e32 v35, v35, v49
	v_fmac_f32_e32 v213, v34, v50
	v_fmac_f32_e32 v35, v34, v48
	v_mul_f32_e32 v34, v37, v45
	v_fmac_f32_e32 v34, v36, v44
	v_mul_f32_e32 v214, v37, v47
	v_add_f32_e32 v34, v35, v34
	v_fmac_f32_e32 v214, v36, v46
	v_add_f32_e32 v212, v212, v34
	s_waitcnt lgkmcnt(0)
	v_mul_f32_e32 v34, v39, v55
	v_mul_f32_e32 v35, v41, v53
	v_add_f32_e32 v213, v213, v214
	v_fmac_f32_e32 v34, v38, v54
	v_fmac_f32_e32 v35, v40, v52
	v_add_f32_e32 v211, v211, v213
	v_add_f32_e32 v34, v34, v35
	v_add_f32_e32 v211, v211, v34
	v_mul_f32_e32 v39, v39, v57
	ds_read_b128 v[34:37], v159
	v_fmac_f32_e32 v39, v38, v56
	v_mul_f32_e32 v38, v41, v43
	v_fmac_f32_e32 v38, v40, v42
	v_add_f32_e32 v38, v39, v38
	v_add_f32_e32 v212, v212, v38
	ds_read_b128 v[38:41], v160
	s_waitcnt lgkmcnt(1)
	v_mul_f32_e32 v213, v35, v107
	v_mul_f32_e32 v35, v35, v95
	v_fmac_f32_e32 v213, v34, v106
	v_fmac_f32_e32 v35, v34, v94
	v_mul_f32_e32 v34, v37, v93
	v_mul_f32_e32 v214, v37, v105
	v_fmac_f32_e32 v34, v36, v92
	v_fmac_f32_e32 v214, v36, v104
	v_add_f32_e32 v34, v35, v34
	v_add_f32_e32 v213, v213, v214
	v_add_f32_e32 v214, 0, v34
	s_waitcnt lgkmcnt(0)
	v_mul_f32_e32 v34, v39, v109
	v_mul_f32_e32 v35, v41, v97
	v_fmac_f32_e32 v34, v38, v108
	v_fmac_f32_e32 v35, v40, v96
	v_add_f32_e32 v213, 0, v213
	v_add_f32_e32 v34, v34, v35
	v_add_f32_e32 v213, v213, v34
	v_mul_f32_e32 v39, v39, v85
	ds_read_b128 v[34:37], v161
	v_fmac_f32_e32 v39, v38, v84
	v_mul_f32_e32 v38, v41, v83
	v_fmac_f32_e32 v38, v40, v82
	v_add_f32_e32 v38, v39, v38
	v_add_f32_e32 v214, v214, v38
	ds_read_b128 v[38:41], v162
	s_waitcnt lgkmcnt(1)
	v_mul_f32_e32 v215, v35, v87
	v_mul_f32_e32 v35, v35, v79
	v_fmac_f32_e32 v215, v34, v86
	v_fmac_f32_e32 v35, v34, v78
	v_mul_f32_e32 v34, v37, v75
	v_fmac_f32_e32 v34, v36, v74
	v_mul_f32_e32 v216, v37, v77
	v_add_f32_e32 v34, v35, v34
	v_fmac_f32_e32 v216, v36, v76
	v_add_f32_e32 v214, v214, v34
	s_waitcnt lgkmcnt(0)
	v_mul_f32_e32 v34, v39, v89
	v_mul_f32_e32 v35, v41, v81
	v_add_f32_e32 v215, v215, v216
	v_fmac_f32_e32 v34, v38, v88
	v_fmac_f32_e32 v35, v40, v80
	v_add_f32_e32 v213, v213, v215
	v_add_f32_e32 v34, v34, v35
	v_add_f32_e32 v213, v213, v34
	v_mul_f32_e32 v39, v39, v69
	ds_read_b128 v[34:37], v163
	v_fmac_f32_e32 v39, v38, v68
	v_mul_f32_e32 v38, v41, v67
	v_fmac_f32_e32 v38, v40, v66
	v_add_f32_e32 v38, v39, v38
	v_add_f32_e32 v214, v214, v38
	ds_read_b128 v[38:41], v164
	s_waitcnt lgkmcnt(1)
	v_mul_f32_e32 v215, v35, v71
	v_mul_f32_e32 v35, v35, v63
	v_fmac_f32_e32 v215, v34, v70
	v_fmac_f32_e32 v35, v34, v62
	v_mul_f32_e32 v34, v37, v59
	v_fmac_f32_e32 v34, v36, v58
	v_mul_f32_e32 v216, v37, v61
	v_add_f32_e32 v34, v35, v34
	v_fmac_f32_e32 v216, v36, v60
	v_add_f32_e32 v214, v214, v34
	s_waitcnt lgkmcnt(0)
	v_mul_f32_e32 v34, v39, v113
	v_mul_f32_e32 v35, v41, v111
	v_add_f32_e32 v215, v215, v216
	v_fmac_f32_e32 v34, v38, v112
	v_fmac_f32_e32 v35, v40, v110
	v_add_f32_e32 v213, v213, v215
	v_add_f32_e32 v34, v34, v35
	v_add_f32_e32 v213, v213, v34
	v_mul_f32_e32 v39, v39, v73
	ds_read_b128 v[34:37], v165
	v_fmac_f32_e32 v39, v38, v72
	v_mul_f32_e32 v38, v41, v65
	v_fmac_f32_e32 v38, v40, v64
	v_add_f32_e32 v38, v39, v38
	v_add_f32_e32 v214, v214, v38
	ds_read_b128 v[38:41], v166
	s_waitcnt lgkmcnt(1)
	v_mul_f32_e32 v215, v35, v51
	v_mul_f32_e32 v35, v35, v49
	v_fmac_f32_e32 v215, v34, v50
	v_fmac_f32_e32 v35, v34, v48
	v_mul_f32_e32 v34, v37, v45
	v_fmac_f32_e32 v34, v36, v44
	v_mul_f32_e32 v216, v37, v47
	v_add_f32_e32 v34, v35, v34
	v_fmac_f32_e32 v216, v36, v46
	v_add_f32_e32 v214, v214, v34
	s_waitcnt lgkmcnt(0)
	v_mul_f32_e32 v34, v39, v55
	v_mul_f32_e32 v35, v41, v53
	v_add_f32_e32 v215, v215, v216
	v_fmac_f32_e32 v34, v38, v54
	v_fmac_f32_e32 v35, v40, v52
	v_add_f32_e32 v213, v213, v215
	v_add_f32_e32 v34, v34, v35
	v_add_f32_e32 v213, v213, v34
	v_mul_f32_e32 v39, v39, v57
	ds_read_b128 v[34:37], v167
	v_fmac_f32_e32 v39, v38, v56
	v_mul_f32_e32 v38, v41, v43
	v_fmac_f32_e32 v38, v40, v42
	v_add_f32_e32 v38, v39, v38
	v_add_f32_e32 v214, v214, v38
	ds_read_b128 v[38:41], v168
	s_waitcnt lgkmcnt(1)
	v_mul_f32_e32 v215, v35, v107
	v_mul_f32_e32 v35, v35, v95
	v_fmac_f32_e32 v215, v34, v106
	v_fmac_f32_e32 v35, v34, v94
	v_mul_f32_e32 v34, v37, v93
	v_mul_f32_e32 v216, v37, v105
	v_fmac_f32_e32 v34, v36, v92
	v_fmac_f32_e32 v216, v36, v104
	v_add_f32_e32 v34, v35, v34
	v_add_f32_e32 v215, v215, v216
	v_add_f32_e32 v216, 0, v34
	s_waitcnt lgkmcnt(0)
	v_mul_f32_e32 v34, v39, v109
	v_mul_f32_e32 v35, v41, v97
	v_fmac_f32_e32 v34, v38, v108
	v_fmac_f32_e32 v35, v40, v96
	v_add_f32_e32 v215, 0, v215
	v_add_f32_e32 v34, v34, v35
	v_add_f32_e32 v215, v215, v34
	v_mul_f32_e32 v39, v39, v85
	ds_read_b128 v[34:37], v169
	v_fmac_f32_e32 v39, v38, v84
	v_mul_f32_e32 v38, v41, v83
	v_fmac_f32_e32 v38, v40, v82
	v_add_f32_e32 v38, v39, v38
	v_add_f32_e32 v216, v216, v38
	ds_read_b128 v[38:41], v172
	s_waitcnt lgkmcnt(1)
	v_mul_f32_e32 v217, v35, v87
	v_mul_f32_e32 v35, v35, v79
	v_fmac_f32_e32 v217, v34, v86
	v_fmac_f32_e32 v35, v34, v78
	v_mul_f32_e32 v34, v37, v75
	v_fmac_f32_e32 v34, v36, v74
	v_mul_f32_e32 v218, v37, v77
	v_add_f32_e32 v34, v35, v34
	v_fmac_f32_e32 v218, v36, v76
	v_add_f32_e32 v216, v216, v34
	s_waitcnt lgkmcnt(0)
	v_mul_f32_e32 v34, v39, v89
	v_mul_f32_e32 v35, v41, v81
	v_add_f32_e32 v217, v217, v218
	v_fmac_f32_e32 v34, v38, v88
	v_fmac_f32_e32 v35, v40, v80
	v_add_f32_e32 v215, v215, v217
	v_add_f32_e32 v34, v34, v35
	v_add_f32_e32 v215, v215, v34
	v_mul_f32_e32 v39, v39, v69
	ds_read_b128 v[34:37], v173
	v_fmac_f32_e32 v39, v38, v68
	v_mul_f32_e32 v38, v41, v67
	v_fmac_f32_e32 v38, v40, v66
	v_add_f32_e32 v38, v39, v38
	v_add_f32_e32 v216, v216, v38
	ds_read_b128 v[38:41], v174
	s_waitcnt lgkmcnt(1)
	v_mul_f32_e32 v217, v35, v71
	v_mul_f32_e32 v35, v35, v63
	v_fmac_f32_e32 v217, v34, v70
	v_fmac_f32_e32 v35, v34, v62
	v_mul_f32_e32 v34, v37, v59
	v_fmac_f32_e32 v34, v36, v58
	v_mul_f32_e32 v218, v37, v61
	v_add_f32_e32 v34, v35, v34
	v_fmac_f32_e32 v218, v36, v60
	v_add_f32_e32 v216, v216, v34
	s_waitcnt lgkmcnt(0)
	v_mul_f32_e32 v34, v39, v113
	v_mul_f32_e32 v35, v41, v111
	v_add_f32_e32 v217, v217, v218
	v_fmac_f32_e32 v34, v38, v112
	v_fmac_f32_e32 v35, v40, v110
	v_add_f32_e32 v215, v215, v217
	v_add_f32_e32 v34, v34, v35
	v_add_f32_e32 v215, v215, v34
	v_mul_f32_e32 v39, v39, v73
	ds_read_b128 v[34:37], v175
	v_fmac_f32_e32 v39, v38, v72
	v_mul_f32_e32 v38, v41, v65
	v_fmac_f32_e32 v38, v40, v64
	v_add_f32_e32 v38, v39, v38
	v_add_f32_e32 v216, v216, v38
	ds_read_b128 v[38:41], v176
	s_waitcnt lgkmcnt(1)
	v_mul_f32_e32 v217, v35, v51
	v_mul_f32_e32 v35, v35, v49
	v_fmac_f32_e32 v217, v34, v50
	v_fmac_f32_e32 v35, v34, v48
	v_mul_f32_e32 v34, v37, v45
	v_fmac_f32_e32 v34, v36, v44
	v_mul_f32_e32 v218, v37, v47
	v_add_f32_e32 v34, v35, v34
	v_fmac_f32_e32 v218, v36, v46
	v_add_f32_e32 v216, v216, v34
	s_waitcnt lgkmcnt(0)
	v_mul_f32_e32 v34, v39, v55
	v_mul_f32_e32 v35, v41, v53
	v_add_f32_e32 v217, v217, v218
	v_fmac_f32_e32 v34, v38, v54
	v_fmac_f32_e32 v35, v40, v52
	v_add_f32_e32 v215, v215, v217
	v_add_f32_e32 v34, v34, v35
	v_add_f32_e32 v215, v215, v34
	v_mul_f32_e32 v39, v39, v57
	ds_read_b128 v[34:37], v177
	v_fmac_f32_e32 v39, v38, v56
	v_mul_f32_e32 v38, v41, v43
	v_fmac_f32_e32 v38, v40, v42
	v_add_f32_e32 v38, v39, v38
	v_add_f32_e32 v216, v216, v38
	ds_read_b128 v[38:41], v178
	s_waitcnt lgkmcnt(1)
	v_mul_f32_e32 v107, v35, v107
	v_mul_f32_e32 v35, v35, v95
	v_fmac_f32_e32 v107, v34, v106
	v_fmac_f32_e32 v35, v34, v94
	v_mul_f32_e32 v34, v37, v93
	v_fmac_f32_e32 v34, v36, v92
	v_mul_f32_e32 v105, v37, v105
	v_add_f32_e32 v34, v35, v34
	v_fmac_f32_e32 v105, v36, v104
	v_add_f32_e32 v92, 0, v34
	s_waitcnt lgkmcnt(0)
	v_mul_f32_e32 v34, v39, v109
	v_mul_f32_e32 v35, v41, v97
	v_add_f32_e32 v104, v107, v105
	v_fmac_f32_e32 v34, v38, v108
	v_fmac_f32_e32 v35, v40, v96
	v_add_f32_e32 v104, 0, v104
	v_add_f32_e32 v34, v34, v35
	v_add_f32_e32 v93, v104, v34
	v_mul_f32_e32 v39, v39, v85
	ds_read_b128 v[34:37], v179
	v_fmac_f32_e32 v39, v38, v84
	v_mul_f32_e32 v38, v41, v83
	v_fmac_f32_e32 v38, v40, v82
	v_add_f32_e32 v38, v39, v38
	v_add_f32_e32 v82, v92, v38
	ds_read_b128 v[38:41], v180
	s_waitcnt lgkmcnt(1)
	v_mul_f32_e32 v83, v35, v87
	v_mul_f32_e32 v35, v35, v79
	v_fmac_f32_e32 v83, v34, v86
	v_fmac_f32_e32 v35, v34, v78
	v_mul_f32_e32 v34, v37, v75
	v_fmac_f32_e32 v34, v36, v74
	v_mul_f32_e32 v77, v37, v77
	v_add_f32_e32 v34, v35, v34
	v_fmac_f32_e32 v77, v36, v76
	v_add_f32_e32 v74, v82, v34
	s_waitcnt lgkmcnt(0)
	v_mul_f32_e32 v34, v39, v89
	v_mul_f32_e32 v35, v41, v81
	v_add_f32_e32 v76, v83, v77
	v_fmac_f32_e32 v34, v38, v88
	v_fmac_f32_e32 v35, v40, v80
	v_add_f32_e32 v76, v93, v76
	v_add_f32_e32 v34, v34, v35
	v_add_f32_e32 v75, v76, v34
	ds_read_b128 v[34:37], v181
	v_mul_f32_e32 v39, v39, v69
	v_fmac_f32_e32 v39, v38, v68
	v_mul_f32_e32 v38, v41, v67
	v_fmac_f32_e32 v38, v40, v66
	ds_read_b128 v[66:69], v182
	v_add_f32_e32 v38, v39, v38
	s_waitcnt lgkmcnt(1)
	v_mul_f32_e32 v39, v35, v71
	v_mul_f32_e32 v35, v35, v63
	v_fmac_f32_e32 v39, v34, v70
	v_fmac_f32_e32 v35, v34, v62
	v_mul_f32_e32 v34, v37, v59
	v_mul_f32_e32 v40, v37, v61
	v_fmac_f32_e32 v34, v36, v58
	v_fmac_f32_e32 v40, v36, v60
	v_add_f32_e32 v34, v35, v34
	s_waitcnt lgkmcnt(0)
	v_mul_f32_e32 v35, v67, v113
	v_mul_f32_e32 v36, v69, v111
	v_add_f32_e32 v39, v39, v40
	v_fmac_f32_e32 v35, v66, v112
	v_fmac_f32_e32 v36, v68, v110
	v_add_f32_e32 v38, v74, v38
	v_add_f32_e32 v39, v75, v39
	v_add_f32_e32 v35, v35, v36
	v_add_f32_e32 v34, v38, v34
	v_add_f32_e32 v58, v39, v35
	ds_read_b128 v[38:41], v183
	v_mul_f32_e32 v35, v67, v73
	v_mul_f32_e32 v36, v69, v65
	v_fmac_f32_e32 v35, v66, v72
	v_fmac_f32_e32 v36, v68, v64
	v_add_f32_e32 v35, v35, v36
	v_add_f32_e32 v59, v34, v35
	ds_read_b128 v[34:37], v184
	s_waitcnt lgkmcnt(1)
	v_mul_f32_e32 v51, v39, v51
	v_mul_f32_e32 v39, v39, v49
	v_fmac_f32_e32 v51, v38, v50
	v_fmac_f32_e32 v39, v38, v48
	v_mul_f32_e32 v38, v41, v45
	v_fmac_f32_e32 v38, v40, v44
	v_mul_f32_e32 v47, v41, v47
	v_add_f32_e32 v38, v39, v38
	v_fmac_f32_e32 v47, v40, v46
	v_add_f32_e32 v39, v59, v38
	s_waitcnt lgkmcnt(0)
	v_mul_f32_e32 v38, v35, v55
	v_mul_f32_e32 v40, v37, v53
	v_fmac_f32_e32 v38, v34, v54
	v_fmac_f32_e32 v40, v36, v52
	v_add_f32_e32 v38, v38, v40
	v_mul_f32_e32 v35, v35, v57
	v_and_b32_e32 v40, 64, v188
	v_fmac_f32_e32 v35, v34, v56
	v_mul_f32_e32 v34, v37, v43
	v_xor_b32_e32 v37, 32, v188
	v_add_u32_e32 v40, 64, v40
	v_cmp_lt_i32_e32 vcc, v37, v40
	v_cndmask_b32_e64 v41, v116, v118, s[14:15]
	v_fmac_f32_e32 v34, v36, v42
	v_cndmask_b32_e32 v37, v188, v37, vcc
	v_lshlrev_b32_e32 v37, 2, v37
	ds_bpermute_b32 v41, v37, v41
	v_add_f32_e32 v34, v35, v34
	v_add_f32_e32 v34, v39, v34
	v_cndmask_b32_e64 v35, v118, v116, s[14:15]
	v_cndmask_b32_e64 v39, v189, v190, s[14:15]
	s_waitcnt lgkmcnt(0)
	v_add_f32_e32 v35, v35, v41
	ds_bpermute_b32 v39, v37, v39
	v_cndmask_b32_e64 v41, v191, v192, s[14:15]
	v_add_f32_e32 v46, v51, v47
	ds_bpermute_b32 v41, v37, v41
	v_cndmask_b32_e64 v44, v193, v194, s[14:15]
	v_add_f32_e32 v46, v58, v46
	ds_bpermute_b32 v44, v37, v44
	v_cndmask_b32_e64 v45, v195, v196, s[14:15]
	v_add_f32_e32 v38, v46, v38
	ds_bpermute_b32 v45, v37, v45
	v_cndmask_b32_e64 v46, v197, v198, s[14:15]
	v_cndmask_b32_e64 v36, v190, v189, s[14:15]
	ds_bpermute_b32 v46, v37, v46
	v_cndmask_b32_e64 v47, v199, v200, s[14:15]
	v_cndmask_b32_e64 v48, v201, v202, s[14:15]
	v_cndmask_b32_e64 v49, v203, v204, s[14:15]
	v_cndmask_b32_e64 v50, v205, v206, s[14:15]
	v_cndmask_b32_e64 v51, v207, v208, s[14:15]
	v_cndmask_b32_e64 v52, v209, v210, s[14:15]
	v_cndmask_b32_e64 v53, v211, v212, s[14:15]
	v_cndmask_b32_e64 v54, v213, v214, s[14:15]
	v_cndmask_b32_e64 v55, v215, v216, s[14:15]
	v_cndmask_b32_e64 v56, v38, v34, s[14:15]
	s_waitcnt lgkmcnt(4)
	v_add_f32_e32 v36, v36, v39
	v_cndmask_b32_e64 v39, v192, v191, s[14:15]
	ds_bpermute_b32 v47, v37, v47
	ds_bpermute_b32 v48, v37, v48
	ds_bpermute_b32 v49, v37, v49
	ds_bpermute_b32 v50, v37, v50
	ds_bpermute_b32 v51, v37, v51
	ds_bpermute_b32 v52, v37, v52
	ds_bpermute_b32 v53, v37, v53
	ds_bpermute_b32 v54, v37, v54
	ds_bpermute_b32 v55, v37, v55
	ds_bpermute_b32 v37, v37, v56
	s_waitcnt lgkmcnt(13)
	v_add_f32_e32 v39, v39, v41
	v_cndmask_b32_e64 v41, v194, v193, s[14:15]
	s_waitcnt lgkmcnt(12)
	v_add_f32_e32 v41, v41, v44
	v_cndmask_b32_e64 v44, v196, v195, s[14:15]
	s_waitcnt lgkmcnt(11)
	v_add_f32_e32 v44, v44, v45
	v_cndmask_b32_e64 v45, v198, v197, s[14:15]
	s_waitcnt lgkmcnt(10)
	v_add_f32_e32 v45, v45, v46
	v_cndmask_b32_e64 v46, v200, v199, s[14:15]
	v_cndmask_b32_e64 v34, v34, v38, s[14:15]
	s_waitcnt lgkmcnt(9)
	v_add_f32_e32 v46, v46, v47
	v_cndmask_b32_e64 v47, v202, v201, s[14:15]
	s_waitcnt lgkmcnt(0)
	v_add_f32_e32 v34, v34, v37
	v_xor_b32_e32 v37, 16, v188
	v_add_f32_e32 v47, v47, v48
	v_cndmask_b32_e64 v48, v204, v203, s[14:15]
	v_cmp_lt_i32_e32 vcc, v37, v40
	v_add_f32_e32 v48, v48, v49
	v_cndmask_b32_e64 v49, v206, v205, s[14:15]
	v_cndmask_b32_e32 v37, v188, v37, vcc
	v_add_f32_e32 v49, v49, v50
	v_lshlrev_b32_e32 v37, 2, v37
	v_cndmask_b32_e64 v38, v48, v35, s[4:5]
	v_cndmask_b32_e64 v35, v35, v48, s[4:5]
	v_cndmask_b32_e64 v50, v208, v207, s[14:15]
	ds_bpermute_b32 v35, v37, v35
	v_cndmask_b32_e64 v48, v36, v49, s[4:5]
	v_add_f32_e32 v50, v50, v51
	v_cndmask_b32_e64 v51, v210, v209, s[14:15]
	ds_bpermute_b32 v48, v37, v48
	v_add_f32_e32 v51, v51, v52
	v_cndmask_b32_e64 v52, v212, v211, s[14:15]
	v_add_f32_e32 v52, v52, v53
	v_cndmask_b32_e64 v53, v214, v213, s[14:15]
	v_add_f32_e32 v53, v53, v54
	v_cndmask_b32_e64 v54, v216, v215, s[14:15]
	v_add_f32_e32 v54, v54, v55
	v_cndmask_b32_e64 v55, v39, v50, s[4:5]
	s_waitcnt lgkmcnt(1)
	v_add_f32_e32 v35, v38, v35
	v_cndmask_b32_e64 v36, v49, v36, s[4:5]
	v_cndmask_b32_e64 v38, v50, v39, s[4:5]
	v_cndmask_b32_e64 v39, v51, v41, s[4:5]
	v_cndmask_b32_e64 v41, v41, v51, s[4:5]
	s_waitcnt lgkmcnt(0)
	v_add_f32_e32 v36, v36, v48
	ds_bpermute_b32 v41, v37, v41
	v_cndmask_b32_e64 v48, v44, v52, s[4:5]
	ds_bpermute_b32 v48, v37, v48
	v_cndmask_b32_e64 v49, v45, v53, s[4:5]
	ds_bpermute_b32 v49, v37, v49
	s_waitcnt lgkmcnt(2)
	v_add_f32_e32 v39, v39, v41
	v_cndmask_b32_e64 v41, v52, v44, s[4:5]
	s_waitcnt lgkmcnt(1)
	v_add_f32_e32 v41, v41, v48
	v_cndmask_b32_e64 v44, v53, v45, s[4:5]
	v_cndmask_b32_e64 v45, v54, v46, s[4:5]
	v_cndmask_b32_e64 v46, v46, v54, s[4:5]
	v_cndmask_b32_e64 v48, v47, v34, s[4:5]
	ds_bpermute_b32 v55, v37, v55
	ds_bpermute_b32 v46, v37, v46
	ds_bpermute_b32 v37, v37, v48
	v_xor_b32_e32 v48, 8, v188
	v_cmp_lt_i32_e32 vcc, v48, v40
	s_waitcnt lgkmcnt(3)
	v_add_f32_e32 v44, v44, v49
	v_cndmask_b32_e64 v34, v34, v47, s[4:5]
	v_cndmask_b32_e32 v48, v188, v48, vcc
	s_waitcnt lgkmcnt(2)
	v_add_f32_e32 v38, v38, v55
	v_lshlrev_b32_e32 v48, 2, v48
	s_waitcnt lgkmcnt(1)
	v_add_f32_e32 v45, v45, v46
	s_waitcnt lgkmcnt(0)
	v_add_f32_e32 v34, v34, v37
	v_cndmask_b32_e64 v37, v44, v36, s[6:7]
	v_cndmask_b32_e64 v36, v36, v44, s[6:7]
	v_cndmask_b32_e64 v49, v35, v41, s[6:7]
	v_cndmask_b32_e64 v35, v41, v35, s[6:7]
	ds_bpermute_b32 v36, v48, v36
	v_cndmask_b32_e64 v41, v38, v45, s[6:7]
	ds_bpermute_b32 v41, v48, v41
	v_cndmask_b32_e64 v44, v39, v34, s[6:7]
	ds_bpermute_b32 v49, v48, v49
	ds_bpermute_b32 v44, v48, v44
	s_waitcnt lgkmcnt(3)
	v_add_f32_e32 v37, v37, v36
	v_cndmask_b32_e64 v36, v45, v38, s[6:7]
	s_waitcnt lgkmcnt(2)
	v_add_f32_e32 v38, v36, v41
	v_xor_b32_e32 v36, 4, v188
	v_cndmask_b32_e64 v34, v34, v39, s[6:7]
	v_cmp_lt_i32_e32 vcc, v36, v40
	s_waitcnt lgkmcnt(1)
	v_add_f32_e32 v35, v35, v49
	s_waitcnt lgkmcnt(0)
	v_add_f32_e32 v34, v34, v44
	v_cndmask_b32_e32 v36, v188, v36, vcc
	v_lshlrev_b32_e32 v36, 2, v36
	v_cndmask_b32_e64 v39, v35, v38, s[8:9]
	v_cndmask_b32_e64 v41, v37, v34, s[8:9]
	ds_bpermute_b32 v39, v36, v39
	ds_bpermute_b32 v41, v36, v41
	v_cndmask_b32_e64 v35, v38, v35, s[8:9]
	v_xor_b32_e32 v38, 2, v188
	v_cndmask_b32_e64 v34, v34, v37, s[8:9]
	v_cmp_lt_i32_e32 vcc, v38, v40
	s_waitcnt lgkmcnt(1)
	v_add_f32_e32 v35, v35, v39
	s_waitcnt lgkmcnt(0)
	v_add_f32_e32 v34, v34, v41
	v_cndmask_b32_e32 v38, v188, v38, vcc
	v_cndmask_b32_e64 v37, v35, v34, s[10:11]
	v_lshlrev_b32_e32 v38, 2, v38
	ds_bpermute_b32 v37, v38, v37
	v_cndmask_b32_e64 v34, v34, v35, s[10:11]
	v_xor_b32_e32 v35, 1, v188
	v_cmp_lt_i32_e32 vcc, v35, v40
	v_bfe_u32 v38, v42, 16, 1
	s_waitcnt lgkmcnt(0)
	v_add_f32_e32 v34, v34, v37
	v_cndmask_b32_e32 v35, v188, v35, vcc
	v_lshlrev_b32_e32 v35, 2, v35
	ds_bpermute_b32 v35, v35, v34
	v_add3_u32 v38, v42, v38, s27
	v_bfe_u32 v37, v43, 16, 1
	v_lshrrev_b32_e32 v38, 16, v38
	v_add3_u32 v37, v43, v37, s27
	v_and_or_b32 v36, v115, s30, v114
	v_and_or_b32 v37, v37, s30, v38
	global_store_dwordx2 v[90:91], v[36:37], off offset:3584
	s_and_saveexec_b64 s[16:17], s[12:13]
	s_cbranch_execz .LBB0_24
	s_waitcnt lgkmcnt(0)
	v_add_f32_e32 v36, v34, v35
	v_add_u32_e32 v34, s26, v117
	v_ashrrev_i32_e32 v35, 31, v34
	v_lshlrev_b64 v[34:35], 6, v[34:35]
	v_lshl_add_u64 v[34:35], v[98:99], 0, v[34:35]
	global_store_dword v[34:35], v36, off
	s_branch .LBB0_24

.LBB0_268:
	s_mov_b32 s5, 0
	s_lshl_b64 s[14:15], s[4:5], 2
	s_add_u32 s12, s12, s14
	s_waitcnt vmcnt(0)
	v_add_u32_e32 v10, s2, v1
	v_mov_b32_e32 v43, 0
	s_addc_u32 s13, s13, s15
	v_lshlrev_b32_e32 v42, 2, v52
	v_lshl_add_u64 v[12:13], s[12:13], 0, v[42:43]
	v_mad_u64_u32 v[2:3], s[12:13], s10, v10, 0
	v_mov_b32_e32 v4, v3
	v_mad_u64_u32 v[4:5], s[12:13], s11, v10, v[4:5]
	v_add_u32_e32 v7, 2, v10
	v_mov_b32_e32 v3, v4
	v_mad_u64_u32 v[4:5], s[12:13], s10, v7, 0
	v_mov_b32_e32 v6, v5
	v_mad_u64_u32 v[6:7], s[12:13], s11, v7, v[6:7]
	v_add_u32_e32 v9, 4, v10
	v_mov_b32_e32 v5, v6
	v_mad_u64_u32 v[6:7], s[12:13], s10, v9, 0
	v_mov_b32_e32 v8, v7
	v_mad_u64_u32 v[8:9], s[12:13], s11, v9, v[8:9]
	v_add_u32_e32 v11, 6, v10
	v_mov_b32_e32 v7, v8
	v_mad_u64_u32 v[8:9], s[12:13], s10, v11, 0
	v_mov_b32_e32 v14, v9
	v_mad_u64_u32 v[14:15], s[12:13], s11, v11, v[14:15]
	v_add_u32_e32 v11, 8, v10
	v_mov_b32_e32 v9, v14
	v_mad_u64_u32 v[14:15], s[12:13], s10, v11, 0
	v_mov_b32_e32 v16, v15
	v_mad_u64_u32 v[16:17], s[12:13], s11, v11, v[16:17]
	v_add_u32_e32 v11, 10, v10
	v_mov_b32_e32 v15, v16
	v_mad_u64_u32 v[16:17], s[12:13], s10, v11, 0
	v_mov_b32_e32 v18, v17
	v_mad_u64_u32 v[18:19], s[12:13], s11, v11, v[18:19]
	v_add_u32_e32 v11, 12, v10
	v_mov_b32_e32 v17, v18
	v_mad_u64_u32 v[18:19], s[12:13], s10, v11, 0
	v_mov_b32_e32 v20, v19
	v_mad_u64_u32 v[20:21], s[12:13], s11, v11, v[20:21]
	v_add_u32_e32 v11, 14, v10
	v_mov_b32_e32 v19, v20
	v_mad_u64_u32 v[20:21], s[12:13], s10, v11, 0
	v_mov_b32_e32 v22, v21
	v_mad_u64_u32 v[22:23], s[12:13], s11, v11, v[22:23]
	v_lshl_add_u64 v[2:3], v[2:3], 2, v[12:13]
	v_lshl_add_u64 v[4:5], v[4:5], 2, v[12:13]
	v_lshl_add_u64 v[6:7], v[6:7], 2, v[12:13]
	v_lshl_add_u64 v[8:9], v[8:9], 2, v[12:13]
	v_lshl_add_u64 v[14:15], v[14:15], 2, v[12:13]
	v_mov_b32_e32 v21, v22
	v_add_u32_e32 v11, 16, v10
	v_lshl_add_u64 v[16:17], v[16:17], 2, v[12:13]
	v_lshl_add_u64 v[18:19], v[18:19], 2, v[12:13]
	v_lshl_add_u64 v[20:21], v[20:21], 2, v[12:13]
	global_load_dword v2, v[2:3], off nt
	s_nop 0
	global_load_dword v3, v[4:5], off nt
	s_nop 0
	global_load_dword v4, v[6:7], off nt
	global_load_dword v5, v[8:9], off nt
	s_nop 0
	global_load_dword v6, v[14:15], off nt
	global_load_dword v7, v[16:17], off nt
	global_load_dword v8, v[18:19], off nt
	global_load_dword v9, v[20:21], off nt
	v_mad_u64_u32 v[14:15], s[12:13], s10, v11, 0
	v_mov_b32_e32 v16, v15
	v_mad_u64_u32 v[16:17], s[12:13], s11, v11, v[16:17]
	v_add_u32_e32 v11, 18, v10
	v_mov_b32_e32 v15, v16
	v_mad_u64_u32 v[16:17], s[12:13], s10, v11, 0
	v_mov_b32_e32 v18, v17
	v_mad_u64_u32 v[18:19], s[12:13], s11, v11, v[18:19]
	v_add_u32_e32 v11, 20, v10
	v_mov_b32_e32 v17, v18
	v_mad_u64_u32 v[18:19], s[12:13], s10, v11, 0
	v_mov_b32_e32 v20, v19
	v_mad_u64_u32 v[20:21], s[12:13], s11, v11, v[20:21]
	v_add_u32_e32 v11, 22, v10
	v_mov_b32_e32 v19, v20
	v_mad_u64_u32 v[20:21], s[12:13], s10, v11, 0
	v_mov_b32_e32 v22, v21
	v_mad_u64_u32 v[22:23], s[12:13], s11, v11, v[22:23]
	v_add_u32_e32 v11, 24, v10
	v_mov_b32_e32 v21, v22
	v_mad_u64_u32 v[22:23], s[12:13], s10, v11, 0
	v_mov_b32_e32 v24, v23
	v_mad_u64_u32 v[24:25], s[12:13], s11, v11, v[24:25]
	v_add_u32_e32 v11, 26, v10
	v_mov_b32_e32 v23, v24
	v_mad_u64_u32 v[24:25], s[12:13], s10, v11, 0
	v_mov_b32_e32 v26, v25
	v_mad_u64_u32 v[26:27], s[12:13], s11, v11, v[26:27]
	v_add_u32_e32 v11, 28, v10
	v_mov_b32_e32 v25, v26
	v_mad_u64_u32 v[26:27], s[12:13], s10, v11, 0
	v_mov_b32_e32 v28, v27
	v_mad_u64_u32 v[28:29], s[12:13], s11, v11, v[28:29]
	v_add_u32_e32 v11, 30, v10
	v_mov_b32_e32 v27, v28
	v_mad_u64_u32 v[28:29], s[12:13], s10, v11, 0
	v_mov_b32_e32 v30, v29
	v_mad_u64_u32 v[30:31], s[12:13], s11, v11, v[30:31]
	v_lshl_add_u64 v[14:15], v[14:15], 2, v[12:13]
	v_mov_b32_e32 v29, v30
	v_add_u32_e32 v11, 32, v10
	v_lshl_add_u64 v[16:17], v[16:17], 2, v[12:13]
	v_lshl_add_u64 v[18:19], v[18:19], 2, v[12:13]
	v_lshl_add_u64 v[20:21], v[20:21], 2, v[12:13]
	v_lshl_add_u64 v[22:23], v[22:23], 2, v[12:13]
	v_lshl_add_u64 v[24:25], v[24:25], 2, v[12:13]
	v_lshl_add_u64 v[26:27], v[26:27], 2, v[12:13]
	v_lshl_add_u64 v[28:29], v[28:29], 2, v[12:13]
	global_load_dword v44, v[14:15], off nt
	global_load_dword v45, v[16:17], off nt
	global_load_dword v46, v[18:19], off nt
	global_load_dword v47, v[20:21], off nt
	global_load_dword v48, v[22:23], off nt
	global_load_dword v49, v[24:25], off nt
	global_load_dword v50, v[26:27], off nt
	global_load_dword v51, v[28:29], off nt
	v_mad_u64_u32 v[14:15], s[12:13], s10, v11, 0
	v_mov_b32_e32 v16, v15
	v_mad_u64_u32 v[16:17], s[12:13], s11, v11, v[16:17]
	v_add_u32_e32 v11, 34, v10
	v_mov_b32_e32 v15, v16
	v_mad_u64_u32 v[16:17], s[12:13], s10, v11, 0
	v_mov_b32_e32 v18, v17
	v_mad_u64_u32 v[18:19], s[12:13], s11, v11, v[18:19]
	v_add_u32_e32 v11, 36, v10
	v_mov_b32_e32 v17, v18
	v_mad_u64_u32 v[18:19], s[12:13], s10, v11, 0
	v_mov_b32_e32 v20, v19
	v_mad_u64_u32 v[20:21], s[12:13], s11, v11, v[20:21]
	v_add_u32_e32 v11, 38, v10
	v_mov_b32_e32 v19, v20
	v_mad_u64_u32 v[20:21], s[12:13], s10, v11, 0
	v_mov_b32_e32 v22, v21
	v_mad_u64_u32 v[22:23], s[12:13], s11, v11, v[22:23]
	v_add_u32_e32 v11, 40, v10
	v_mov_b32_e32 v21, v22
	v_mad_u64_u32 v[22:23], s[12:13], s10, v11, 0
	v_mov_b32_e32 v24, v23
	v_mad_u64_u32 v[24:25], s[12:13], s11, v11, v[24:25]
	v_add_u32_e32 v11, 42, v10
	v_mov_b32_e32 v23, v24
	v_mad_u64_u32 v[24:25], s[12:13], s10, v11, 0
	v_mov_b32_e32 v26, v25
	v_mad_u64_u32 v[26:27], s[12:13], s11, v11, v[26:27]
	v_add_u32_e32 v11, 44, v10
	v_mov_b32_e32 v25, v26
	v_mad_u64_u32 v[26:27], s[12:13], s10, v11, 0
	v_mov_b32_e32 v28, v27
	v_mad_u64_u32 v[28:29], s[12:13], s11, v11, v[28:29]
	v_add_u32_e32 v11, 46, v10
	v_mov_b32_e32 v27, v28
	v_mad_u64_u32 v[28:29], s[12:13], s10, v11, 0
	v_mov_b32_e32 v30, v29
	v_mad_u64_u32 v[30:31], s[12:13], s11, v11, v[30:31]
	v_lshl_add_u64 v[14:15], v[14:15], 2, v[12:13]
	v_mov_b32_e32 v29, v30
	v_add_u32_e32 v11, 48, v10
	v_lshl_add_u64 v[16:17], v[16:17], 2, v[12:13]
	v_lshl_add_u64 v[18:19], v[18:19], 2, v[12:13]
	v_lshl_add_u64 v[20:21], v[20:21], 2, v[12:13]
	v_lshl_add_u64 v[22:23], v[22:23], 2, v[12:13]
	v_lshl_add_u64 v[24:25], v[24:25], 2, v[12:13]
	v_lshl_add_u64 v[26:27], v[26:27], 2, v[12:13]
	v_lshl_add_u64 v[28:29], v[28:29], 2, v[12:13]
	global_load_dword v56, v[14:15], off nt
	global_load_dword v57, v[16:17], off nt
	global_load_dword v58, v[18:19], off nt
	global_load_dword v59, v[20:21], off nt
	global_load_dword v60, v[22:23], off nt
	global_load_dword v61, v[24:25], off nt
	global_load_dword v94, v[26:27], off nt
	global_load_dword v95, v[28:29], off nt
	v_mad_u64_u32 v[14:15], s[12:13], s10, v11, 0
	v_mov_b32_e32 v16, v15
	v_mad_u64_u32 v[16:17], s[12:13], s11, v11, v[16:17]
	v_add_u32_e32 v11, 50, v10
	v_mov_b32_e32 v15, v16
	v_mad_u64_u32 v[16:17], s[12:13], s10, v11, 0
	v_mov_b32_e32 v18, v17
	v_mad_u64_u32 v[18:19], s[12:13], s11, v11, v[18:19]
	v_add_u32_e32 v11, 52, v10
	v_mov_b32_e32 v17, v18
	v_mad_u64_u32 v[18:19], s[12:13], s10, v11, 0
	v_mov_b32_e32 v20, v19
	v_mad_u64_u32 v[20:21], s[12:13], s11, v11, v[20:21]
	v_add_u32_e32 v11, 54, v10
	v_mov_b32_e32 v19, v20
	v_mad_u64_u32 v[20:21], s[12:13], s10, v11, 0
	v_mov_b32_e32 v22, v21
	v_mad_u64_u32 v[22:23], s[12:13], s11, v11, v[22:23]
	v_add_u32_e32 v11, 56, v10
	v_mov_b32_e32 v21, v22
	v_mad_u64_u32 v[22:23], s[12:13], s10, v11, 0
	v_mov_b32_e32 v24, v23
	v_mad_u64_u32 v[24:25], s[12:13], s11, v11, v[24:25]
	v_add_u32_e32 v11, 58, v10
	v_mov_b32_e32 v23, v24
	v_mad_u64_u32 v[24:25], s[12:13], s10, v11, 0
	v_mov_b32_e32 v26, v25
	v_mad_u64_u32 v[26:27], s[12:13], s11, v11, v[26:27]
	v_add_u32_e32 v11, 60, v10
	v_mov_b32_e32 v25, v26
	v_mad_u64_u32 v[26:27], s[12:13], s10, v11, 0
	v_mov_b32_e32 v28, v27
	v_mad_u64_u32 v[28:29], s[12:13], s11, v11, v[28:29]
	v_add_u32_e32 v11, 62, v10
	v_mov_b32_e32 v27, v28
	v_mad_u64_u32 v[28:29], s[12:13], s10, v11, 0
	v_mov_b32_e32 v30, v29
	v_mad_u64_u32 v[30:31], s[10:11], s11, v11, v[30:31]
	v_lshl_add_u64 v[14:15], v[14:15], 2, v[12:13]
	v_mov_b32_e32 v29, v30
	v_lshl_add_u64 v[16:17], v[16:17], 2, v[12:13]
	v_lshl_add_u64 v[18:19], v[18:19], 2, v[12:13]
	v_lshl_add_u64 v[20:21], v[20:21], 2, v[12:13]
	v_lshl_add_u64 v[22:23], v[22:23], 2, v[12:13]
	v_lshl_add_u64 v[24:25], v[24:25], 2, v[12:13]
	v_lshl_add_u64 v[26:27], v[26:27], 2, v[12:13]
	v_lshl_add_u64 v[12:13], v[28:29], 2, v[12:13]
	global_load_dword v96, v[14:15], off nt
	global_load_dword v97, v[16:17], off nt
	global_load_dword v98, v[18:19], off nt
	global_load_dword v99, v[20:21], off nt
	global_load_dword v100, v[22:23], off nt
	global_load_dword v101, v[24:25], off nt
	global_load_dword v102, v[26:27], off nt
	global_load_dword v103, v[12:13], off nt
	s_cmp_eq_u64 s[8:9], 0
	s_mov_b64 s[16:17], 0
	s_cbranch_scc1 .LBB0_270
	v_mov_b32_e32 v11, v43
	v_lshl_add_u64 v[54:55], v[10:11], 2, s[8:9]
	global_load_dword v10, v[54:55], off nt
	global_load_dword v11, v[54:55], off offset:8 nt
	global_load_dword v12, v[54:55], off offset:16 nt
	global_load_dword v13, v[54:55], off offset:24 nt
	global_load_dword v14, v[54:55], off offset:32 nt
	global_load_dword v15, v[54:55], off offset:40 nt
	global_load_dword v16, v[54:55], off offset:48 nt
	global_load_dword v17, v[54:55], off offset:56 nt
	global_load_dword v18, v[54:55], off offset:64 nt
	global_load_dword v19, v[54:55], off offset:72 nt
	global_load_dword v20, v[54:55], off offset:80 nt
	global_load_dword v21, v[54:55], off offset:88 nt
	global_load_dword v22, v[54:55], off offset:96 nt
	global_load_dword v23, v[54:55], off offset:104 nt
	global_load_dword v24, v[54:55], off offset:112 nt
	global_load_dword v25, v[54:55], off offset:120 nt
	global_load_dword v26, v[54:55], off offset:128 nt
	global_load_dword v27, v[54:55], off offset:136 nt
	global_load_dword v28, v[54:55], off offset:144 nt
	global_load_dword v29, v[54:55], off offset:152 nt
	global_load_dword v30, v[54:55], off offset:160 nt
	global_load_dword v31, v[54:55], off offset:168 nt
	global_load_dword v32, v[54:55], off offset:176 nt
	global_load_dword v33, v[54:55], off offset:184 nt
	global_load_dword v34, v[54:55], off offset:192 nt
	global_load_dword v35, v[54:55], off offset:200 nt
	global_load_dword v36, v[54:55], off offset:208 nt
	global_load_dword v37, v[54:55], off offset:216 nt
	global_load_dword v38, v[54:55], off offset:224 nt
	global_load_dword v39, v[54:55], off offset:232 nt
	global_load_dword v40, v[54:55], off offset:240 nt
	global_load_dword v41, v[54:55], off offset:248 nt
	s_mov_b64 s[16:17], s[8:9]
	s_branch .LBB0_271

.LBB0_283:
	s_ashr_i32 s11, s10, 31
	s_lshl_b64 s[36:37], s[10:11], 2
	v_add_u32_e32 v136, s8, v1
	s_add_u32 s34, s34, s36
	s_addc_u32 s35, s35, s37
	v_ashrrev_i32_e32 v137, 31, v136
	v_lshl_add_u64 v[128:129], v[42:43], 2, s[34:35]
	v_mul_lo_u32 v54, s20, v137
	v_mul_lo_u32 v106, s21, v136
	v_mad_u64_u32 v[104:105], s[34:35], s20, v136, 0
	v_add3_u32 v105, v105, v54, v106
	v_add_u32_e32 v54, 2, v136
	v_ashrrev_i32_e32 v106, 31, v54
	v_mul_lo_u32 v108, s20, v106
	v_mul_lo_u32 v109, s21, v54
	v_mad_u64_u32 v[106:107], s[34:35], s20, v54, 0
	v_add_u32_e32 v54, 4, v136
	v_add3_u32 v107, v107, v108, v109
	v_ashrrev_i32_e32 v108, 31, v54
	v_mul_lo_u32 v110, s20, v108
	v_mul_lo_u32 v111, s21, v54
	v_mad_u64_u32 v[108:109], s[34:35], s20, v54, 0
	v_add_u32_e32 v54, 6, v136
	v_add3_u32 v109, v109, v110, v111
	v_ashrrev_i32_e32 v110, 31, v54
	v_mul_lo_u32 v112, s20, v110
	v_mul_lo_u32 v113, s21, v54
	v_mad_u64_u32 v[110:111], s[34:35], s20, v54, 0
	v_add_u32_e32 v54, 8, v136
	v_add3_u32 v111, v111, v112, v113
	v_ashrrev_i32_e32 v112, 31, v54
	v_mul_lo_u32 v114, s20, v112
	v_mul_lo_u32 v115, s21, v54
	v_mad_u64_u32 v[112:113], s[34:35], s20, v54, 0
	v_add_u32_e32 v54, 10, v136
	v_add3_u32 v113, v113, v114, v115
	v_ashrrev_i32_e32 v114, 31, v54
	v_mul_lo_u32 v116, s20, v114
	v_mul_lo_u32 v117, s21, v54
	v_mad_u64_u32 v[114:115], s[34:35], s20, v54, 0
	v_add_u32_e32 v54, 12, v136
	v_add3_u32 v115, v115, v116, v117
	v_ashrrev_i32_e32 v116, 31, v54
	v_mul_lo_u32 v118, s20, v116
	v_mul_lo_u32 v119, s21, v54
	v_mad_u64_u32 v[116:117], s[34:35], s20, v54, 0
	v_add_u32_e32 v54, 14, v136
	v_add3_u32 v117, v117, v118, v119
	v_ashrrev_i32_e32 v118, 31, v54
	v_mul_lo_u32 v120, s20, v118
	v_mul_lo_u32 v121, s21, v54
	v_mad_u64_u32 v[118:119], s[34:35], s20, v54, 0
	v_lshl_add_u64 v[104:105], v[104:105], 2, v[128:129]
	v_lshl_add_u64 v[106:107], v[106:107], 2, v[128:129]
	v_lshl_add_u64 v[108:109], v[108:109], 2, v[128:129]
	v_lshl_add_u64 v[110:111], v[110:111], 2, v[128:129]
	v_lshl_add_u64 v[112:113], v[112:113], 2, v[128:129]
	v_add3_u32 v119, v119, v120, v121
	v_add_u32_e32 v54, 16, v136
	v_lshl_add_u64 v[114:115], v[114:115], 2, v[128:129]
	v_lshl_add_u64 v[116:117], v[116:117], 2, v[128:129]
	v_lshl_add_u64 v[118:119], v[118:119], 2, v[128:129]
	global_load_dword v105, v[104:105], off nt
	s_nop 0
	global_load_dword v104, v[106:107], off nt
	s_nop 0
	global_load_dword v107, v[108:109], off nt
	global_load_dword v106, v[110:111], off nt
	s_nop 0
	global_load_dword v109, v[112:113], off nt
	global_load_dword v108, v[114:115], off nt
	global_load_dword v111, v[116:117], off nt
	global_load_dword v110, v[118:119], off nt
	v_ashrrev_i32_e32 v112, 31, v54
	v_mul_lo_u32 v114, s20, v112
	v_mul_lo_u32 v115, s21, v54
	v_mad_u64_u32 v[112:113], s[34:35], s20, v54, 0
	v_add_u32_e32 v54, 18, v136
	v_add3_u32 v113, v113, v114, v115
	v_ashrrev_i32_e32 v114, 31, v54
	v_mul_lo_u32 v116, s20, v114
	v_mul_lo_u32 v117, s21, v54
	v_mad_u64_u32 v[114:115], s[34:35], s20, v54, 0
	v_add_u32_e32 v54, 20, v136
	v_add3_u32 v115, v115, v116, v117
	v_ashrrev_i32_e32 v116, 31, v54
	v_mul_lo_u32 v118, s20, v116
	v_mul_lo_u32 v119, s21, v54
	v_mad_u64_u32 v[116:117], s[34:35], s20, v54, 0
	v_add_u32_e32 v54, 22, v136
	v_add3_u32 v117, v117, v118, v119
	v_ashrrev_i32_e32 v118, 31, v54
	v_mul_lo_u32 v120, s20, v118
	v_mul_lo_u32 v121, s21, v54
	v_mad_u64_u32 v[118:119], s[34:35], s20, v54, 0
	v_add_u32_e32 v54, 24, v136
	v_add3_u32 v119, v119, v120, v121
	v_ashrrev_i32_e32 v120, 31, v54
	v_mul_lo_u32 v122, s20, v120
	v_mul_lo_u32 v123, s21, v54
	v_mad_u64_u32 v[120:121], s[34:35], s20, v54, 0
	v_add_u32_e32 v54, 26, v136
	v_add3_u32 v121, v121, v122, v123
	v_ashrrev_i32_e32 v122, 31, v54
	v_mul_lo_u32 v124, s20, v122
	v_mul_lo_u32 v125, s21, v54
	v_mad_u64_u32 v[122:123], s[34:35], s20, v54, 0
	v_add_u32_e32 v54, 28, v136
	v_add3_u32 v123, v123, v124, v125
	v_ashrrev_i32_e32 v124, 31, v54
	v_mul_lo_u32 v126, s20, v124
	v_mul_lo_u32 v127, s21, v54
	v_mad_u64_u32 v[124:125], s[34:35], s20, v54, 0
	v_add_u32_e32 v54, 30, v136
	v_add3_u32 v125, v125, v126, v127
	v_ashrrev_i32_e32 v126, 31, v54
	v_mul_lo_u32 v130, s20, v126
	v_mul_lo_u32 v131, s21, v54
	v_mad_u64_u32 v[126:127], s[34:35], s20, v54, 0
	v_lshl_add_u64 v[112:113], v[112:113], 2, v[128:129]
	v_lshl_add_u64 v[114:115], v[114:115], 2, v[128:129]
	v_lshl_add_u64 v[116:117], v[116:117], 2, v[128:129]
	v_lshl_add_u64 v[118:119], v[118:119], 2, v[128:129]
	v_lshl_add_u64 v[120:121], v[120:121], 2, v[128:129]
	v_add3_u32 v127, v127, v130, v131
	v_add_u32_e32 v54, 32, v136
	v_lshl_add_u64 v[122:123], v[122:123], 2, v[128:129]
	v_lshl_add_u64 v[124:125], v[124:125], 2, v[128:129]
	v_lshl_add_u64 v[126:127], v[126:127], 2, v[128:129]
	global_load_dword v113, v[112:113], off nt
	s_nop 0
	global_load_dword v112, v[114:115], off nt
	s_nop 0
	global_load_dword v115, v[116:117], off nt
	global_load_dword v114, v[118:119], off nt
	s_nop 0
	global_load_dword v117, v[120:121], off nt
	global_load_dword v116, v[122:123], off nt
	global_load_dword v119, v[124:125], off nt
	global_load_dword v118, v[126:127], off nt
	v_ashrrev_i32_e32 v120, 31, v54
	v_mul_lo_u32 v122, s20, v120
	v_mul_lo_u32 v123, s21, v54
	v_mad_u64_u32 v[120:121], s[34:35], s20, v54, 0
	v_add_u32_e32 v54, 34, v136
	v_add3_u32 v121, v121, v122, v123
	v_ashrrev_i32_e32 v122, 31, v54
	v_mul_lo_u32 v124, s20, v122
	v_mul_lo_u32 v125, s21, v54
	v_mad_u64_u32 v[122:123], s[34:35], s20, v54, 0
	v_add_u32_e32 v54, 36, v136
	v_add3_u32 v123, v123, v124, v125
	v_ashrrev_i32_e32 v124, 31, v54
	v_mul_lo_u32 v126, s20, v124
	v_mul_lo_u32 v127, s21, v54
	v_mad_u64_u32 v[124:125], s[34:35], s20, v54, 0
	v_add_u32_e32 v54, 38, v136
	v_add3_u32 v125, v125, v126, v127
	v_ashrrev_i32_e32 v126, 31, v54
	v_mul_lo_u32 v130, s20, v126
	v_mul_lo_u32 v131, s21, v54
	v_mad_u64_u32 v[126:127], s[34:35], s20, v54, 0
	v_add_u32_e32 v54, 40, v136
	v_add3_u32 v127, v127, v130, v131
	v_ashrrev_i32_e32 v130, 31, v54
	v_mul_lo_u32 v132, s20, v130
	v_mul_lo_u32 v133, s21, v54
	v_mad_u64_u32 v[130:131], s[34:35], s20, v54, 0
	v_add_u32_e32 v54, 42, v136
	v_add3_u32 v131, v131, v132, v133
	v_ashrrev_i32_e32 v132, 31, v54
	v_mul_lo_u32 v134, s20, v132
	v_mul_lo_u32 v135, s21, v54
	v_mad_u64_u32 v[132:133], s[34:35], s20, v54, 0
	v_add_u32_e32 v54, 44, v136
	v_add3_u32 v133, v133, v134, v135
	v_ashrrev_i32_e32 v134, 31, v54
	v_mul_lo_u32 v143, s20, v134
	v_mul_lo_u32 v144, s21, v54
	v_mad_u64_u32 v[134:135], s[34:35], s20, v54, 0
	v_add_u32_e32 v54, 46, v136
	v_add3_u32 v135, v135, v143, v144
	v_ashrrev_i32_e32 v143, 31, v54
	v_mul_lo_u32 v143, s20, v143
	v_mul_lo_u32 v146, s21, v54
	v_mad_u64_u32 v[144:145], s[34:35], s20, v54, 0
	v_lshl_add_u64 v[120:121], v[120:121], 2, v[128:129]
	v_lshl_add_u64 v[122:123], v[122:123], 2, v[128:129]
	v_lshl_add_u64 v[124:125], v[124:125], 2, v[128:129]
	v_lshl_add_u64 v[126:127], v[126:127], 2, v[128:129]
	v_lshl_add_u64 v[130:131], v[130:131], 2, v[128:129]
	v_add3_u32 v145, v145, v143, v146
	v_add_u32_e32 v54, 48, v136
	v_lshl_add_u64 v[132:133], v[132:133], 2, v[128:129]
	v_lshl_add_u64 v[134:135], v[134:135], 2, v[128:129]
	v_lshl_add_u64 v[144:145], v[144:145], 2, v[128:129]
	global_load_dword v121, v[120:121], off nt
	s_nop 0
	global_load_dword v120, v[122:123], off nt
	s_nop 0
	global_load_dword v123, v[124:125], off nt
	global_load_dword v122, v[126:127], off nt
	s_nop 0
	global_load_dword v125, v[130:131], off nt
	global_load_dword v124, v[132:133], off nt
	global_load_dword v127, v[134:135], off nt
	global_load_dword v126, v[144:145], off nt
	v_ashrrev_i32_e32 v130, 31, v54
	v_mul_lo_u32 v132, s20, v130
	v_mul_lo_u32 v133, s21, v54
	v_mad_u64_u32 v[130:131], s[34:35], s20, v54, 0
	v_add_u32_e32 v54, 50, v136
	v_add3_u32 v131, v131, v132, v133
	v_ashrrev_i32_e32 v132, 31, v54
	v_mul_lo_u32 v134, s20, v132
	v_mul_lo_u32 v135, s21, v54
	v_mad_u64_u32 v[132:133], s[34:35], s20, v54, 0
	v_add_u32_e32 v54, 52, v136
	v_add3_u32 v133, v133, v134, v135
	v_ashrrev_i32_e32 v134, 31, v54
	v_mul_lo_u32 v143, s20, v134
	v_mul_lo_u32 v144, s21, v54
	v_mad_u64_u32 v[134:135], s[34:35], s20, v54, 0
	v_add_u32_e32 v54, 54, v136
	v_add3_u32 v135, v135, v143, v144
	v_ashrrev_i32_e32 v143, 31, v54
	v_mul_lo_u32 v143, s20, v143
	v_mul_lo_u32 v146, s21, v54
	v_mad_u64_u32 v[144:145], s[34:35], s20, v54, 0
	v_add_u32_e32 v54, 56, v136
	v_add3_u32 v145, v145, v143, v146
	v_ashrrev_i32_e32 v143, 31, v54
	v_mul_lo_u32 v143, s20, v143
	v_mul_lo_u32 v148, s21, v54
	v_mad_u64_u32 v[146:147], s[34:35], s20, v54, 0
	v_add_u32_e32 v54, 58, v136
	v_add3_u32 v147, v147, v143, v148
	v_ashrrev_i32_e32 v143, 31, v54
	v_mul_lo_u32 v143, s20, v143
	v_mul_lo_u32 v150, s21, v54
	v_mad_u64_u32 v[148:149], s[34:35], s20, v54, 0
	v_add_u32_e32 v54, 60, v136
	v_add3_u32 v149, v149, v143, v150
	v_ashrrev_i32_e32 v143, 31, v54
	v_mul_lo_u32 v143, s20, v143
	v_mul_lo_u32 v152, s21, v54
	v_mad_u64_u32 v[150:151], s[34:35], s20, v54, 0
	v_add_u32_e32 v54, 62, v136
	v_add3_u32 v151, v151, v143, v152
	v_ashrrev_i32_e32 v143, 31, v54
	v_mul_lo_u32 v143, s20, v143
	v_mul_lo_u32 v154, s21, v54
	v_mad_u64_u32 v[152:153], s[20:21], s20, v54, 0
	v_lshl_add_u64 v[130:131], v[130:131], 2, v[128:129]
	v_lshl_add_u64 v[132:133], v[132:133], 2, v[128:129]
	v_lshl_add_u64 v[134:135], v[134:135], 2, v[128:129]
	v_add3_u32 v153, v153, v143, v154
	v_lshl_add_u64 v[144:145], v[144:145], 2, v[128:129]
	v_lshl_add_u64 v[146:147], v[146:147], 2, v[128:129]
	v_lshl_add_u64 v[148:149], v[148:149], 2, v[128:129]
	v_lshl_add_u64 v[150:151], v[150:151], 2, v[128:129]
	v_lshl_add_u64 v[152:153], v[152:153], 2, v[128:129]
	global_load_dword v129, v[130:131], off nt
	global_load_dword v128, v[132:133], off nt
	s_nop 0
	global_load_dword v131, v[134:135], off nt
	global_load_dword v130, v[144:145], off nt
	global_load_dword v133, v[146:147], off nt
	global_load_dword v132, v[148:149], off nt
	s_nop 0
	global_load_dword v135, v[150:151], off nt
	global_load_dword v134, v[152:153], off nt
	s_cmp_eq_u64 s[22:23], 0
	s_mov_b64 s[20:21], 0
	s_cbranch_scc1 .LBB0_285
	v_lshl_add_u64 v[136:137], v[136:137], 2, s[22:23]
	global_load_dword v63, v[136:137], off nt
	global_load_dword v62, v[136:137], off offset:8 nt
	global_load_dword v65, v[136:137], off offset:16 nt
	global_load_dword v64, v[136:137], off offset:24 nt
	global_load_dword v67, v[136:137], off offset:32 nt
	global_load_dword v66, v[136:137], off offset:40 nt
	global_load_dword v69, v[136:137], off offset:48 nt
	global_load_dword v68, v[136:137], off offset:56 nt
	global_load_dword v71, v[136:137], off offset:64 nt
	global_load_dword v70, v[136:137], off offset:72 nt
	global_load_dword v73, v[136:137], off offset:80 nt
	global_load_dword v72, v[136:137], off offset:88 nt
	global_load_dword v75, v[136:137], off offset:96 nt
	global_load_dword v74, v[136:137], off offset:104 nt
	global_load_dword v77, v[136:137], off offset:112 nt
	global_load_dword v76, v[136:137], off offset:120 nt
	global_load_dword v79, v[136:137], off offset:128 nt
	global_load_dword v78, v[136:137], off offset:136 nt
	global_load_dword v81, v[136:137], off offset:144 nt
	global_load_dword v80, v[136:137], off offset:152 nt
	global_load_dword v83, v[136:137], off offset:160 nt
	global_load_dword v82, v[136:137], off offset:168 nt
	global_load_dword v85, v[136:137], off offset:176 nt
	global_load_dword v84, v[136:137], off offset:184 nt
	global_load_dword v87, v[136:137], off offset:192 nt
	global_load_dword v86, v[136:137], off offset:200 nt
	global_load_dword v89, v[136:137], off offset:208 nt
	global_load_dword v88, v[136:137], off offset:216 nt
	global_load_dword v91, v[136:137], off offset:224 nt
	global_load_dword v90, v[136:137], off offset:232 nt
	global_load_dword v93, v[136:137], off offset:240 nt
	global_load_dword v92, v[136:137], off offset:248 nt
	s_mov_b64 s[20:21], s[22:23]

.LBB0_297:
	s_ashr_i32 s5, s4, 31
	s_lshl_b64 s[36:37], s[4:5], 2
	v_add_u32_e32 v136, s2, v1
	s_add_u32 s34, s34, s36
	s_addc_u32 s35, s35, s37
	v_ashrrev_i32_e32 v137, 31, v136
	v_lshl_add_u64 v[96:97], v[42:43], 2, s[34:35]
	v_mul_lo_u32 v4, s16, v137
	v_mul_lo_u32 v5, s17, v136
	v_mad_u64_u32 v[2:3], s[34:35], s16, v136, 0
	v_add3_u32 v3, v3, v4, v5
	v_add_u32_e32 v4, 2, v136
	v_ashrrev_i32_e32 v5, 31, v4
	v_mul_lo_u32 v6, s16, v5
	v_mul_lo_u32 v7, s17, v4
	v_mad_u64_u32 v[4:5], s[34:35], s16, v4, 0
	v_add3_u32 v5, v5, v6, v7
	v_add_u32_e32 v6, 4, v136
	v_ashrrev_i32_e32 v7, 31, v6
	v_mul_lo_u32 v8, s16, v7
	v_mul_lo_u32 v9, s17, v6
	v_mad_u64_u32 v[6:7], s[34:35], s16, v6, 0
	v_add3_u32 v7, v7, v8, v9
	v_add_u32_e32 v8, 6, v136
	v_ashrrev_i32_e32 v9, 31, v8
	v_mul_lo_u32 v44, s16, v9
	v_mul_lo_u32 v45, s17, v8
	v_mad_u64_u32 v[8:9], s[34:35], s16, v8, 0
	v_add3_u32 v9, v9, v44, v45
	v_add_u32_e32 v44, 8, v136
	v_ashrrev_i32_e32 v45, 31, v44
	v_mul_lo_u32 v46, s16, v45
	v_mul_lo_u32 v47, s17, v44
	v_mad_u64_u32 v[44:45], s[34:35], s16, v44, 0
	v_add3_u32 v45, v45, v46, v47
	v_add_u32_e32 v46, 10, v136
	v_ashrrev_i32_e32 v47, 31, v46
	v_mul_lo_u32 v48, s16, v47
	v_mul_lo_u32 v49, s17, v46
	v_mad_u64_u32 v[46:47], s[34:35], s16, v46, 0
	v_add3_u32 v47, v47, v48, v49
	v_add_u32_e32 v48, 12, v136
	v_ashrrev_i32_e32 v49, 31, v48
	v_mul_lo_u32 v50, s16, v49
	v_mul_lo_u32 v51, s17, v48
	v_mad_u64_u32 v[48:49], s[34:35], s16, v48, 0
	v_add3_u32 v49, v49, v50, v51
	v_add_u32_e32 v50, 14, v136
	v_ashrrev_i32_e32 v51, 31, v50
	v_mul_lo_u32 v56, s16, v51
	v_mul_lo_u32 v57, s17, v50
	v_mad_u64_u32 v[50:51], s[34:35], s16, v50, 0
	v_lshl_add_u64 v[2:3], v[2:3], 2, v[96:97]
	v_lshl_add_u64 v[4:5], v[4:5], 2, v[96:97]
	v_lshl_add_u64 v[6:7], v[6:7], 2, v[96:97]
	v_lshl_add_u64 v[8:9], v[8:9], 2, v[96:97]
	v_lshl_add_u64 v[44:45], v[44:45], 2, v[96:97]
	v_add3_u32 v51, v51, v56, v57
	v_lshl_add_u64 v[46:47], v[46:47], 2, v[96:97]
	v_lshl_add_u64 v[48:49], v[48:49], 2, v[96:97]
	v_lshl_add_u64 v[50:51], v[50:51], 2, v[96:97]
	global_load_dword v2, v[2:3], off nt
	s_nop 0
	global_load_dword v3, v[4:5], off nt
	s_nop 0
	global_load_dword v4, v[6:7], off nt
	global_load_dword v5, v[8:9], off nt
	s_nop 0
	global_load_dword v6, v[44:45], off nt
	global_load_dword v7, v[46:47], off nt
	global_load_dword v8, v[48:49], off nt
	global_load_dword v9, v[50:51], off nt
	v_add_u32_e32 v44, 16, v136
	v_ashrrev_i32_e32 v45, 31, v44
	v_mul_lo_u32 v46, s16, v45
	v_mul_lo_u32 v47, s17, v44
	v_mad_u64_u32 v[44:45], s[34:35], s16, v44, 0
	v_add3_u32 v45, v45, v46, v47
	v_add_u32_e32 v46, 18, v136
	v_ashrrev_i32_e32 v47, 31, v46
	v_mul_lo_u32 v48, s16, v47
	v_mul_lo_u32 v49, s17, v46
	v_mad_u64_u32 v[46:47], s[34:35], s16, v46, 0
	v_add3_u32 v47, v47, v48, v49
	v_add_u32_e32 v48, 20, v136
	v_ashrrev_i32_e32 v49, 31, v48
	v_mul_lo_u32 v50, s16, v49
	v_mul_lo_u32 v51, s17, v48
	v_mad_u64_u32 v[48:49], s[34:35], s16, v48, 0
	v_add3_u32 v49, v49, v50, v51
	v_add_u32_e32 v50, 22, v136
	v_ashrrev_i32_e32 v51, 31, v50
	v_mul_lo_u32 v56, s16, v51
	v_mul_lo_u32 v57, s17, v50
	v_mad_u64_u32 v[50:51], s[34:35], s16, v50, 0
	v_add3_u32 v51, v51, v56, v57
	v_add_u32_e32 v56, 24, v136
	v_ashrrev_i32_e32 v57, 31, v56
	v_mul_lo_u32 v58, s16, v57
	v_mul_lo_u32 v59, s17, v56
	v_mad_u64_u32 v[56:57], s[34:35], s16, v56, 0
	v_add3_u32 v57, v57, v58, v59
	v_add_u32_e32 v58, 26, v136
	v_ashrrev_i32_e32 v59, 31, v58
	v_mul_lo_u32 v60, s16, v59
	v_mul_lo_u32 v61, s17, v58
	v_mad_u64_u32 v[58:59], s[34:35], s16, v58, 0
	v_add3_u32 v59, v59, v60, v61
	v_add_u32_e32 v60, 28, v136
	v_ashrrev_i32_e32 v61, 31, v60
	v_mul_lo_u32 v94, s16, v61
	v_mul_lo_u32 v95, s17, v60
	v_mad_u64_u32 v[60:61], s[34:35], s16, v60, 0
	v_add3_u32 v61, v61, v94, v95
	v_add_u32_e32 v94, 30, v136
	v_ashrrev_i32_e32 v95, 31, v94
	v_mul_lo_u32 v98, s16, v95
	v_mul_lo_u32 v99, s17, v94
	v_mad_u64_u32 v[94:95], s[34:35], s16, v94, 0
	v_lshl_add_u64 v[44:45], v[44:45], 2, v[96:97]
	v_lshl_add_u64 v[46:47], v[46:47], 2, v[96:97]
	v_lshl_add_u64 v[48:49], v[48:49], 2, v[96:97]
	v_lshl_add_u64 v[50:51], v[50:51], 2, v[96:97]
	v_lshl_add_u64 v[56:57], v[56:57], 2, v[96:97]
	v_add3_u32 v95, v95, v98, v99
	v_lshl_add_u64 v[58:59], v[58:59], 2, v[96:97]
	v_lshl_add_u64 v[60:61], v[60:61], 2, v[96:97]
	v_lshl_add_u64 v[94:95], v[94:95], 2, v[96:97]
	global_load_dword v44, v[44:45], off nt
	s_nop 0
	global_load_dword v45, v[46:47], off nt
	s_nop 0
	global_load_dword v46, v[48:49], off nt
	global_load_dword v47, v[50:51], off nt
	s_nop 0
	global_load_dword v48, v[56:57], off nt
	global_load_dword v49, v[58:59], off nt
	global_load_dword v50, v[60:61], off nt
	global_load_dword v51, v[94:95], off nt
	v_add_u32_e32 v56, 32, v136
	v_ashrrev_i32_e32 v57, 31, v56
	v_mul_lo_u32 v58, s16, v57
	v_mul_lo_u32 v59, s17, v56
	v_mad_u64_u32 v[56:57], s[34:35], s16, v56, 0
	v_add3_u32 v57, v57, v58, v59
	v_add_u32_e32 v58, 34, v136
	v_ashrrev_i32_e32 v59, 31, v58
	v_mul_lo_u32 v60, s16, v59
	v_mul_lo_u32 v61, s17, v58
	v_mad_u64_u32 v[58:59], s[34:35], s16, v58, 0
	v_add3_u32 v59, v59, v60, v61
	v_add_u32_e32 v60, 36, v136
	v_ashrrev_i32_e32 v61, 31, v60
	v_mul_lo_u32 v94, s16, v61
	v_mul_lo_u32 v95, s17, v60
	v_mad_u64_u32 v[60:61], s[34:35], s16, v60, 0
	v_add3_u32 v61, v61, v94, v95
	v_add_u32_e32 v94, 38, v136
	v_ashrrev_i32_e32 v95, 31, v94
	v_mul_lo_u32 v98, s16, v95
	v_mul_lo_u32 v99, s17, v94
	v_mad_u64_u32 v[94:95], s[34:35], s16, v94, 0
	v_add3_u32 v95, v95, v98, v99
	v_add_u32_e32 v98, 40, v136
	v_ashrrev_i32_e32 v99, 31, v98
	v_mul_lo_u32 v100, s16, v99
	v_mul_lo_u32 v101, s17, v98
	v_mad_u64_u32 v[98:99], s[34:35], s16, v98, 0
	v_add3_u32 v99, v99, v100, v101
	v_add_u32_e32 v100, 42, v136
	v_ashrrev_i32_e32 v101, 31, v100
	v_mul_lo_u32 v102, s16, v101
	v_mul_lo_u32 v103, s17, v100
	v_mad_u64_u32 v[100:101], s[34:35], s16, v100, 0
	v_add3_u32 v101, v101, v102, v103
	v_add_u32_e32 v102, 44, v136
	v_ashrrev_i32_e32 v103, 31, v102
	v_mul_lo_u32 v150, s16, v103
	v_mul_lo_u32 v151, s17, v102
	v_mad_u64_u32 v[102:103], s[34:35], s16, v102, 0
	v_add3_u32 v103, v103, v150, v151
	v_add_u32_e32 v150, 46, v136
	v_ashrrev_i32_e32 v151, 31, v150
	v_mul_lo_u32 v152, s16, v151
	v_mul_lo_u32 v153, s17, v150
	v_mad_u64_u32 v[150:151], s[34:35], s16, v150, 0
	v_lshl_add_u64 v[56:57], v[56:57], 2, v[96:97]
	v_lshl_add_u64 v[58:59], v[58:59], 2, v[96:97]
	v_lshl_add_u64 v[60:61], v[60:61], 2, v[96:97]
	v_lshl_add_u64 v[94:95], v[94:95], 2, v[96:97]
	v_lshl_add_u64 v[98:99], v[98:99], 2, v[96:97]
	v_add3_u32 v151, v151, v152, v153
	v_lshl_add_u64 v[100:101], v[100:101], 2, v[96:97]
	v_lshl_add_u64 v[102:103], v[102:103], 2, v[96:97]
	v_lshl_add_u64 v[150:151], v[150:151], 2, v[96:97]
	global_load_dword v56, v[56:57], off nt
	s_nop 0
	global_load_dword v57, v[58:59], off nt
	s_nop 0
	global_load_dword v58, v[60:61], off nt
	global_load_dword v59, v[94:95], off nt
	s_nop 0
	global_load_dword v60, v[98:99], off nt
	global_load_dword v61, v[100:101], off nt
	global_load_dword v94, v[102:103], off nt
	global_load_dword v95, v[150:151], off nt
	v_add_u32_e32 v98, 48, v136
	v_ashrrev_i32_e32 v99, 31, v98
	v_mul_lo_u32 v100, s16, v99
	v_mul_lo_u32 v101, s17, v98
	v_mad_u64_u32 v[98:99], s[34:35], s16, v98, 0
	v_add3_u32 v99, v99, v100, v101
	v_add_u32_e32 v100, 50, v136
	v_ashrrev_i32_e32 v101, 31, v100
	v_mul_lo_u32 v102, s16, v101
	v_mul_lo_u32 v103, s17, v100
	v_mad_u64_u32 v[100:101], s[34:35], s16, v100, 0
	v_add3_u32 v101, v101, v102, v103
	v_add_u32_e32 v102, 52, v136
	v_ashrrev_i32_e32 v103, 31, v102
	v_mul_lo_u32 v150, s16, v103
	v_mul_lo_u32 v151, s17, v102
	v_mad_u64_u32 v[102:103], s[34:35], s16, v102, 0
	v_add3_u32 v103, v103, v150, v151
	v_add_u32_e32 v150, 54, v136
	v_ashrrev_i32_e32 v151, 31, v150
	v_mul_lo_u32 v152, s16, v151
	v_mul_lo_u32 v153, s17, v150
	v_mad_u64_u32 v[150:151], s[34:35], s16, v150, 0
	v_add3_u32 v151, v151, v152, v153
	v_add_u32_e32 v152, 56, v136
	v_ashrrev_i32_e32 v153, 31, v152
	v_mul_lo_u32 v154, s16, v153
	v_mul_lo_u32 v155, s17, v152
	v_mad_u64_u32 v[152:153], s[34:35], s16, v152, 0
	v_add3_u32 v153, v153, v154, v155
	v_add_u32_e32 v154, 58, v136
	v_ashrrev_i32_e32 v155, 31, v154
	v_mul_lo_u32 v156, s16, v155
	v_mul_lo_u32 v157, s17, v154
	v_mad_u64_u32 v[154:155], s[34:35], s16, v154, 0
	v_add3_u32 v155, v155, v156, v157
	v_add_u32_e32 v156, 60, v136
	v_ashrrev_i32_e32 v157, 31, v156
	v_mul_lo_u32 v158, s16, v157
	v_mul_lo_u32 v159, s17, v156
	v_mad_u64_u32 v[156:157], s[34:35], s16, v156, 0
	v_add3_u32 v157, v157, v158, v159
	v_add_u32_e32 v158, 62, v136
	v_ashrrev_i32_e32 v159, 31, v158
	v_mul_lo_u32 v160, s16, v159
	v_mul_lo_u32 v161, s17, v158
	v_mad_u64_u32 v[158:159], s[16:17], s16, v158, 0
	v_lshl_add_u64 v[98:99], v[98:99], 2, v[96:97]
	v_lshl_add_u64 v[100:101], v[100:101], 2, v[96:97]
	v_lshl_add_u64 v[102:103], v[102:103], 2, v[96:97]
	v_add3_u32 v159, v159, v160, v161
	v_lshl_add_u64 v[150:151], v[150:151], 2, v[96:97]
	v_lshl_add_u64 v[152:153], v[152:153], 2, v[96:97]
	v_lshl_add_u64 v[154:155], v[154:155], 2, v[96:97]
	v_lshl_add_u64 v[156:157], v[156:157], 2, v[96:97]
	v_lshl_add_u64 v[158:159], v[158:159], 2, v[96:97]
	global_load_dword v96, v[98:99], off nt
	global_load_dword v97, v[100:101], off nt
	s_nop 0
	global_load_dword v98, v[102:103], off nt
	global_load_dword v99, v[150:151], off nt
	global_load_dword v100, v[152:153], off nt
	global_load_dword v101, v[154:155], off nt
	s_nop 0
	global_load_dword v102, v[156:157], off nt
	global_load_dword v103, v[158:159], off nt
	s_cmp_eq_u64 s[22:23], 0
	s_mov_b64 s[16:17], 0
	s_cbranch_scc1 .LBB0_299
	v_lshl_add_u64 v[136:137], v[136:137], 2, s[22:23]
	global_load_dword v10, v[136:137], off nt
	global_load_dword v11, v[136:137], off offset:8 nt
	global_load_dword v12, v[136:137], off offset:16 nt
	global_load_dword v13, v[136:137], off offset:24 nt
	global_load_dword v14, v[136:137], off offset:32 nt
	global_load_dword v15, v[136:137], off offset:40 nt
	global_load_dword v16, v[136:137], off offset:48 nt
	global_load_dword v17, v[136:137], off offset:56 nt
	global_load_dword v18, v[136:137], off offset:64 nt
	global_load_dword v19, v[136:137], off offset:72 nt
	global_load_dword v20, v[136:137], off offset:80 nt
	global_load_dword v21, v[136:137], off offset:88 nt
	global_load_dword v22, v[136:137], off offset:96 nt
	global_load_dword v23, v[136:137], off offset:104 nt
	global_load_dword v24, v[136:137], off offset:112 nt
	global_load_dword v25, v[136:137], off offset:120 nt
	global_load_dword v26, v[136:137], off offset:128 nt
	global_load_dword v27, v[136:137], off offset:136 nt
	global_load_dword v28, v[136:137], off offset:144 nt
	global_load_dword v29, v[136:137], off offset:152 nt
	global_load_dword v30, v[136:137], off offset:160 nt
	global_load_dword v31, v[136:137], off offset:168 nt
	global_load_dword v32, v[136:137], off offset:176 nt
	global_load_dword v33, v[136:137], off offset:184 nt
	global_load_dword v34, v[136:137], off offset:192 nt
	global_load_dword v35, v[136:137], off offset:200 nt
	global_load_dword v36, v[136:137], off offset:208 nt
	global_load_dword v37, v[136:137], off offset:216 nt
	global_load_dword v38, v[136:137], off offset:224 nt
	global_load_dword v39, v[136:137], off offset:232 nt
	global_load_dword v40, v[136:137], off offset:240 nt
	global_load_dword v41, v[136:137], off offset:248 nt
	s_mov_b64 s[16:17], s[22:23]
